# RG-LRU gate section: per-block parameter vectors prefetched one block ahead into spare registers (8 serial round trips overlapped)
# baseline (speedup 1.0000x reference)
.Llru_tail:
	s_movk_i32 s0, 0x110
	v_ashrrev_i32_e32 v161, 6, v160
	v_and_b32_e32 v162, 31, v160
	v_mul_lo_u32 v33, v36, s0
	v_lshlrev_b32_e32 v34, 2, v37
	v_add3_u32 v33, s89, v33, v34
	v_lshl_or_b32 v163, v161, 5, v162
	s_waitcnt vmcnt(6)
	ds_write_b128 v33, v[4:7]
	ds_write_b128 v33, v[0:3] offset:16
	s_waitcnt vmcnt(4)
	ds_write_b128 v33, v[12:15] offset:32
	ds_write_b128 v33, v[8:11] offset:48
	s_waitcnt vmcnt(2)
	ds_write_b128 v33, v[20:23] offset:64
	ds_write_b128 v33, v[16:19] offset:80
	s_waitcnt vmcnt(0)
	ds_write_b128 v33, v[28:31] offset:96
	ds_write_b128 v33, v[24:27] offset:112
	v_mul_lo_u32 v0, v163, s0
	v_and_b32_e32 v1, 32, v160
	v_add3_u32 v64, s89, v0, v1
	s_waitcnt lgkmcnt(0)
	s_barrier
	ds_read_b128 v[0:3], v64
	ds_read_b128 v[4:7], v64 offset:16
	v_bfe_u32 v32, v160, 5, 1
	v_lshlrev_b32_e32 v168, 4, v32
	v_lshlrev_b32_e32 v100, 7, v162
	s_waitcnt lgkmcnt(1)
	v_cvt_pk_bf16_f32 v56, v0, v1
	v_cvt_pk_bf16_f32 v57, v2, v3
	s_waitcnt lgkmcnt(0)
	v_cvt_pk_bf16_f32 v58, v4, v5
	v_cvt_pk_bf16_f32 v59, v6, v7
	ds_read_b128 v[0:3], v64 offset:64
	ds_read_b128 v[4:7], v64 offset:80
	v_mov_b32_e32 v101, v169
	v_lshlrev_b32_e32 v164, 2, v32
	v_sub_u32_e32 v124, v64, v168
	s_waitcnt lgkmcnt(1)
	v_cvt_pk_bf16_f32 v52, v0, v1
	v_cvt_pk_bf16_f32 v53, v2, v3
	s_waitcnt lgkmcnt(0)
	v_cvt_pk_bf16_f32 v54, v4, v5
	v_cvt_pk_bf16_f32 v55, v6, v7
	ds_read_b128 v[0:3], v64 offset:128
	ds_read_b128 v[4:7], v64 offset:144
	s_waitcnt lgkmcnt(1)
	v_cvt_pk_bf16_f32 v48, v0, v1
	v_cvt_pk_bf16_f32 v49, v2, v3
	s_waitcnt lgkmcnt(0)
	v_cvt_pk_bf16_f32 v50, v4, v5
	v_cvt_pk_bf16_f32 v51, v6, v7
	ds_read_b128 v[0:3], v64 offset:192
	ds_read_b128 v[4:7], v64 offset:208
	s_load_dwordx2 s[6:7], s[54:55], 0x98
	s_load_dwordx4 s[0:3], s[54:55], 0xa8
	s_waitcnt lgkmcnt(0)
	v_cvt_pk_bf16_f32 v44, v0, v1
	s_add_u32 s5, s6, s60
	s_addc_u32 s6, s7, s61
	s_lshl_b32 s75, s74, 2
	s_add_u32 s10, s5, s75
	s_addc_u32 s11, s6, 0
	s_add_u32 s0, s0, s60
	s_addc_u32 s1, s1, s61
	s_add_u32 s12, s0, s75
	s_addc_u32 s13, s1, 0
	s_add_u32 s0, s2, s60
	s_addc_u32 s1, s3, s61
	s_add_u32 s8, s0, s75
	s_addc_u32 s9, s1, 0
	global_load_dwordx4 v[170:173], v168, s[10:11]
	global_load_dwordx2 v[144:145], v168, s[12:13]
	global_load_dwordx2 v[166:167], v168, s[12:13] offset:8
	global_load_dwordx2 v[180:181], v168, s[8:9]
	global_load_dwordx2 v[202:203], v168, s[8:9] offset:8
	s_lshl_b32 s2, s4, 13
	s_add_u32 s0, s36, s2
	s_addc_u32 s1, s37, 0
	v_lshl_add_u64 v[96:97], s[0:1], 0, v[168:169]
	s_add_u32 s0, s38, s2
	s_addc_u32 s1, s39, 0
	v_lshl_add_u64 v[98:99], s[0:1], 0, v[168:169]
	v_lshl_add_u64 v[40:41], v[96:97], 0, v[100:101]
	v_cvt_pk_bf16_f32 v45, v2, v3
	v_cvt_pk_bf16_f32 v46, v4, v5
	v_cvt_pk_bf16_f32 v47, v6, v7
	v_lshl_add_u64 v[42:43], v[98:99], 0, v[100:101]
	global_load_dwordx4 v[0:3], v[40:41], off
	global_load_dwordx4 v[4:7], v[42:43], off
	global_load_dwordx4 v[32:35], v[40:41], off offset:32
	global_load_dwordx4 v[36:39], v[42:43], off offset:32
	s_mov_b32 s0, 0x3f317217
	s_mov_b32 s1, 0x7f800000
	s_mov_b32 s3, 0x3cf5c28f
	s_mov_b32 s2, 0xc1700000
	s_mov_b32 s4, 0xbdcccccd
	s_waitcnt vmcnt(3)
	v_mfma_f32_32x32x16_bf16 v[16:31], v[0:3], v[56:59], 0
	s_waitcnt vmcnt(2)
	v_mfma_f32_32x32x16_bf16 v[0:15], v[4:7], v[56:59], 0
	s_waitcnt vmcnt(1)
	v_mfma_f32_32x32x16_bf16 v[16:31], v[32:35], v[52:55], v[16:31]
	s_waitcnt vmcnt(0)
	v_mfma_f32_32x32x16_bf16 v[0:15], v[36:39], v[52:55], v[0:15]
	global_load_dwordx4 v[32:35], v[40:41], off offset:64
	global_load_dwordx4 v[36:39], v[42:43], off offset:64
	s_waitcnt vmcnt(1)
	v_mfma_f32_32x32x16_bf16 v[16:31], v[32:35], v[48:51], v[16:31]
	s_waitcnt vmcnt(0)
	v_mfma_f32_32x32x16_bf16 v[0:15], v[36:39], v[48:51], v[0:15]
	global_load_dwordx4 v[32:35], v[40:41], off offset:96
	global_load_dwordx4 v[36:39], v[42:43], off offset:96
	s_waitcnt vmcnt(1)
	v_mfma_f32_32x32x16_bf16 v[16:31], v[32:35], v[44:47], v[16:31]
	s_waitcnt vmcnt(0)
	v_mfma_f32_32x32x16_bf16 v[0:15], v[36:39], v[44:47], v[0:15]
	s_waitcnt vmcnt(0)
	s_nop 7
	v_mov_b32_e32 v40, v170
	v_mov_b32_e32 v41, v171
	v_mov_b32_e32 v42, v172
	v_mov_b32_e32 v43, v173
	v_mov_b32_e32 v36, v144
	v_mov_b32_e32 v37, v145
	v_mov_b32_e32 v38, v166
	v_mov_b32_e32 v39, v167
	v_mov_b32_e32 v60, v180
	v_mov_b32_e32 v61, v181
	v_mov_b32_e32 v62, v202
	v_mov_b32_e32 v63, v203
	global_load_dwordx4 v[170:173], v168, s[10:11] offset:32
	global_load_dwordx2 v[144:145], v168, s[12:13] offset:32
	global_load_dwordx2 v[166:167], v168, s[12:13] offset:40
	global_load_dwordx2 v[180:181], v168, s[8:9] offset:32
	global_load_dwordx2 v[202:203], v168, s[8:9] offset:40
	ds_read_b128 v[64:67], v124
	ds_read_b128 v[32:35], v124 offset:32
	s_nop 3
	v_add_f32_e32 v16, v16, v40
	v_add_f32_e32 v0, v0, v36
	v_mul_f32_e32 v36, 0xbfb8aa3b, v60
	v_exp_f32_e32 v36, v36
	v_mul_f32_e32 v16, 0xbfb8aa3b, v16
	v_exp_f32_e32 v16, v16
	v_mul_f32_e32 v0, 0xbfb8aa3b, v0
	v_add_f32_e32 v40, 1.0, v36
	v_cmp_gt_f32_e32 vcc, s28, v40
	v_add_f32_e32 v16, 1.0, v16
	v_rcp_f32_e32 v16, v16
	v_cndmask_b32_e64 v68, 0, 32, vcc
	v_ldexp_f32 v40, v40, v68
	v_log_f32_e32 v40, v40
	v_mul_f32_e32 v16, 0xc1000000, v16
	v_exp_f32_e32 v0, v0
	v_add_f32_e32 v1, v1, v37
	v_mul_f32_e32 v68, 0x3f317217, v40
	v_fma_f32 v68, v40, s0, -v68
	v_fmac_f32_e32 v68, 0x3377d1cf, v40
	v_fmac_f32_e32 v68, 0x3f317217, v40
	v_cmp_lt_f32_e64 s[6:7], |v40|, s1
	v_add_f32_e32 v0, 1.0, v0
	v_rcp_f32_e32 v0, v0
	v_cndmask_b32_e64 v40, v40, v68, s[6:7]
	v_cndmask_b32_e32 v68, 0, v201, vcc
	v_sub_f32_e32 v40, v40, v68
	v_fmamk_f32 v68, v36, 0xbe800000, v188
	v_fma_f32 v68, -v36, v68, 0.5
	v_fma_f32 v68, -v36, v68, 1.0
	v_mul_f32_e32 v68, v36, v68
	v_cmp_gt_f32_e64 s[6:7], s3, v36
	v_cmp_gt_f32_e32 vcc, s2, v60
	s_waitcnt lgkmcnt(1)
	v_mul_f32_e32 v0, v64, v0
	v_cndmask_b32_e64 v36, v40, v68, s[6:7]
	v_cndmask_b32_e64 v36, v36, -v60, vcc
	v_mul_f32_e32 v16, v16, v36
	v_mul_f32_e32 v36, 0x3fb8aa3b, v16
	v_add_f32_e32 v16, v16, v16
	v_mul_f32_e32 v40, 0x3fb8aa3b, v16
	v_exp_f32_e32 v136, v36
	v_fmamk_f32 v36, v16, 0x3c088889, v189
	v_exp_f32_e32 v40, v40
	v_fmaak_f32 v36, v16, v36, 0x3e2aaaab
	v_fma_f32 v36, v16, v36, 0.5
	v_fma_f32 v36, v16, v36, 1.0
	v_mul_f32_e64 v36, v36, -v16
	v_sub_f32_e32 v40, 1.0, v40
	v_cmp_lt_f32_e32 vcc, s4, v16
	v_mul_f32_e32 v1, 0xbfb8aa3b, v1
	v_exp_f32_e32 v1, v1
	v_cndmask_b32_e32 v16, v40, v36, vcc
	v_sqrt_f32_e32 v16, v16
	v_add_f32_e32 v1, 1.0, v1
	v_rcp_f32_e32 v1, v1
	v_mul_f32_e32 v137, v0, v16
	v_mul_f32_e32 v16, 0xbfb8aa3b, v61
	v_exp_f32_e32 v16, v16
	v_add_f32_e32 v0, v17, v41
	v_mul_f32_e32 v0, 0xbfb8aa3b, v0
	v_exp_f32_e32 v0, v0
	v_add_f32_e32 v17, 1.0, v16
	v_cmp_gt_f32_e32 vcc, s28, v17
	v_mul_f32_e32 v1, v65, v1
	v_add_f32_e32 v0, 1.0, v0
	v_cndmask_b32_e64 v36, 0, 32, vcc
	v_ldexp_f32 v17, v17, v36
	v_log_f32_e32 v17, v17
	v_rcp_f32_e32 v0, v0
	v_mul_f32_e32 v36, 0x3f317217, v17
	v_fma_f32 v36, v17, s0, -v36
	v_fmac_f32_e32 v36, 0x3377d1cf, v17
	v_fmac_f32_e32 v36, 0x3f317217, v17
	v_cmp_lt_f32_e64 s[6:7], |v17|, s1
	v_mul_f32_e32 v0, 0xc1000000, v0
	s_nop 0
	v_cndmask_b32_e64 v17, v17, v36, s[6:7]
	v_cndmask_b32_e32 v36, 0, v201, vcc
	v_sub_f32_e32 v17, v17, v36
	v_fmamk_f32 v36, v16, 0xbe800000, v188
	v_fma_f32 v36, -v16, v36, 0.5
	v_fma_f32 v36, -v16, v36, 1.0
	v_mul_f32_e32 v36, v16, v36
	v_cmp_gt_f32_e64 s[6:7], s3, v16
	v_cmp_gt_f32_e32 vcc, s2, v61
	s_nop 0
	v_cndmask_b32_e64 v16, v17, v36, s[6:7]
	v_cndmask_b32_e64 v16, v16, -v61, vcc
	v_mul_f32_e32 v0, v0, v16
	v_mul_f32_e32 v16, 0x3fb8aa3b, v0
	v_add_f32_e32 v0, v0, v0
	v_mul_f32_e32 v17, 0x3fb8aa3b, v0
	v_exp_f32_e32 v138, v16
	v_fmamk_f32 v16, v0, 0x3c088889, v189
	v_exp_f32_e32 v17, v17
	v_fmaak_f32 v16, v0, v16, 0x3e2aaaab
	v_fma_f32 v16, v0, v16, 0.5
	v_fma_f32 v16, v0, v16, 1.0
	v_mul_f32_e64 v16, v16, -v0
	v_sub_f32_e32 v17, 1.0, v17
	v_cmp_lt_f32_e32 vcc, s4, v0
	s_nop 1
	v_cndmask_b32_e32 v0, v17, v16, vcc
	v_sqrt_f32_e32 v0, v0
	s_nop 0
	v_mul_f32_e32 v139, v1, v0
	v_add_f32_e32 v1, v2, v38
	v_mul_f32_e32 v2, 0xbfb8aa3b, v62
	v_exp_f32_e32 v2, v2
	v_add_f32_e32 v0, v18, v42
	v_mul_f32_e32 v0, 0xbfb8aa3b, v0
	v_exp_f32_e32 v0, v0
	v_add_f32_e32 v16, 1.0, v2
	v_cmp_gt_f32_e32 vcc, s28, v16
	v_mul_f32_e32 v1, 0xbfb8aa3b, v1
	v_add_f32_e32 v0, 1.0, v0
	v_cndmask_b32_e64 v17, 0, 32, vcc
	v_ldexp_f32 v16, v16, v17
	v_log_f32_e32 v16, v16
	v_rcp_f32_e32 v0, v0
	v_exp_f32_e32 v1, v1
	v_mul_f32_e32 v17, 0x3f317217, v16
	v_fma_f32 v17, v16, s0, -v17
	v_fmac_f32_e32 v17, 0x3377d1cf, v16
	v_fmac_f32_e32 v17, 0x3f317217, v16
	v_cmp_lt_f32_e64 s[6:7], |v16|, s1
	v_mul_f32_e32 v0, 0xc1000000, v0
	v_add_f32_e32 v1, 1.0, v1
	v_cndmask_b32_e64 v16, v16, v17, s[6:7]
	v_cndmask_b32_e32 v17, 0, v201, vcc
	v_sub_f32_e32 v16, v16, v17
	v_fmamk_f32 v17, v2, 0xbe800000, v188
	v_fma_f32 v17, -v2, v17, 0.5
	v_fma_f32 v17, -v2, v17, 1.0
	v_mul_f32_e32 v17, v2, v17
	v_cmp_gt_f32_e64 s[6:7], s3, v2
	v_cmp_gt_f32_e32 vcc, s2, v62
	v_rcp_f32_e32 v1, v1
	v_cndmask_b32_e64 v2, v16, v17, s[6:7]
	v_cndmask_b32_e64 v2, v2, -v62, vcc
	v_mul_f32_e32 v0, v0, v2
	v_mul_f32_e32 v2, 0x3fb8aa3b, v0
	v_add_f32_e32 v0, v0, v0
	v_mul_f32_e32 v16, 0x3fb8aa3b, v0
	v_exp_f32_e32 v140, v2
	v_fmamk_f32 v2, v0, 0x3c088889, v189
	v_exp_f32_e32 v16, v16
	v_fmaak_f32 v2, v0, v2, 0x3e2aaaab
	v_fma_f32 v2, v0, v2, 0.5
	v_fma_f32 v2, v0, v2, 1.0
	v_mul_f32_e64 v2, v2, -v0
	v_sub_f32_e32 v16, 1.0, v16
	v_cmp_lt_f32_e32 vcc, s4, v0
	v_mul_f32_e32 v1, v66, v1
	s_nop 0
	v_cndmask_b32_e32 v0, v16, v2, vcc
	v_mul_f32_e32 v2, 0xbfb8aa3b, v63
	v_sqrt_f32_e32 v0, v0
	v_exp_f32_e32 v2, v2
	v_mul_f32_e32 v141, v1, v0
	v_add_f32_e32 v1, v3, v39
	v_add_f32_e32 v3, 1.0, v2
	v_cmp_gt_f32_e32 vcc, s28, v3
	v_add_f32_e32 v0, v19, v43
	v_mul_f32_e32 v0, 0xbfb8aa3b, v0
	v_cndmask_b32_e64 v16, 0, 32, vcc
	v_ldexp_f32 v3, v3, v16
	v_log_f32_e32 v3, v3
	v_exp_f32_e32 v0, v0
	v_mul_f32_e32 v1, 0xbfb8aa3b, v1
	v_exp_f32_e32 v1, v1
	v_mul_f32_e32 v16, 0x3f317217, v3
	v_fma_f32 v16, v3, s0, -v16
	v_fmac_f32_e32 v16, 0x3377d1cf, v3
	v_fmac_f32_e32 v16, 0x3f317217, v3
	v_cmp_lt_f32_e64 s[6:7], |v3|, s1
	v_add_f32_e32 v0, 1.0, v0
	v_rcp_f32_e32 v0, v0
	v_cndmask_b32_e64 v3, v3, v16, s[6:7]
	v_cndmask_b32_e32 v16, 0, v201, vcc
	v_sub_f32_e32 v3, v3, v16
	v_fmamk_f32 v16, v2, 0xbe800000, v188
	v_fma_f32 v16, -v2, v16, 0.5
	v_fma_f32 v16, -v2, v16, 1.0
	v_mul_f32_e32 v16, v2, v16
	v_cmp_gt_f32_e64 s[6:7], s3, v2
	v_cmp_gt_f32_e32 vcc, s2, v63
	v_mul_f32_e32 v0, 0xc1000000, v0
	v_cndmask_b32_e64 v2, v3, v16, s[6:7]
	v_cndmask_b32_e64 v2, v2, -v63, vcc
	v_mul_f32_e32 v0, v0, v2
	v_mul_f32_e32 v2, 0x3fb8aa3b, v0
	v_add_f32_e32 v0, v0, v0
	v_mul_f32_e32 v3, 0x3fb8aa3b, v0
	v_exp_f32_e32 v142, v2
	v_fmamk_f32 v2, v0, 0x3c088889, v189
	v_exp_f32_e32 v3, v3
	v_fmaak_f32 v2, v0, v2, 0x3e2aaaab
	v_fma_f32 v2, v0, v2, 0.5
	v_fma_f32 v2, v0, v2, 1.0
	v_add_f32_e32 v1, 1.0, v1
	v_mul_f32_e64 v2, v2, -v0
	v_sub_f32_e32 v3, 1.0, v3
	v_cmp_lt_f32_e32 vcc, s4, v0
	v_rcp_f32_e32 v1, v1
	s_nop 0
	v_cndmask_b32_e32 v0, v3, v2, vcc
	v_sqrt_f32_e32 v0, v0
	v_mul_f32_e32 v1, v67, v1
	v_mul_f32_e32 v143, v1, v0
	s_waitcnt vmcnt(0)
	s_nop 7
	v_mov_b32_e32 v36, v170
	v_mov_b32_e32 v37, v171
	v_mov_b32_e32 v38, v172
	v_mov_b32_e32 v39, v173
	v_mov_b32_e32 v16, v144
	v_mov_b32_e32 v17, v145
	v_mov_b32_e32 v18, v166
	v_mov_b32_e32 v19, v167
	v_mov_b32_e32 v0, v180
	v_mov_b32_e32 v1, v181
	v_mov_b32_e32 v2, v202
	v_mov_b32_e32 v3, v203
	global_load_dwordx4 v[170:173], v168, s[10:11] offset:64
	global_load_dwordx2 v[144:145], v168, s[12:13] offset:64
	global_load_dwordx2 v[166:167], v168, s[12:13] offset:72
	global_load_dwordx2 v[180:181], v168, s[8:9] offset:64
	global_load_dwordx2 v[202:203], v168, s[8:9] offset:72
	v_add_f32_e32 v20, v20, v36
	v_mul_f32_e32 v20, 0xbfb8aa3b, v20
	v_exp_f32_e32 v20, v20
	v_add_f32_e32 v4, v4, v16
	v_mul_f32_e32 v4, 0xbfb8aa3b, v4
	v_exp_f32_e32 v4, v4
	v_add_f32_e32 v20, 1.0, v20
	v_mul_f32_e32 v16, 0xbfb8aa3b, v0
	v_rcp_f32_e32 v20, v20
	v_exp_f32_e32 v16, v16
	v_add_f32_e32 v4, 1.0, v4
	v_rcp_f32_e32 v60, v4
	v_mul_f32_e32 v4, 0xc1000000, v20
	v_add_f32_e32 v20, 1.0, v16
	v_cmp_gt_f32_e32 vcc, s28, v20
	s_nop 1
	v_cndmask_b32_e64 v36, 0, 32, vcc
	v_ldexp_f32 v20, v20, v36
	v_log_f32_e32 v20, v20
	s_nop 0
	v_mul_f32_e32 v36, 0x3f317217, v20
	v_fma_f32 v36, v20, s0, -v36
	v_fmac_f32_e32 v36, 0x3377d1cf, v20
	v_fmac_f32_e32 v36, 0x3f317217, v20
	v_cmp_lt_f32_e64 s[6:7], |v20|, s1
	s_nop 1
	v_cndmask_b32_e64 v20, v20, v36, s[6:7]
	v_cndmask_b32_e32 v36, 0, v201, vcc
	v_sub_f32_e32 v20, v20, v36
	v_fmamk_f32 v36, v16, 0xbe800000, v188
	v_fma_f32 v36, -v16, v36, 0.5
	v_fma_f32 v36, -v16, v36, 1.0
	v_mul_f32_e32 v36, v16, v36
	v_cmp_gt_f32_e64 s[6:7], s3, v16
	v_cmp_gt_f32_e32 vcc, s2, v0
	s_nop 0
	v_cndmask_b32_e64 v16, v20, v36, s[6:7]
	v_cndmask_b32_e64 v0, v16, -v0, vcc
	v_mul_f32_e32 v0, v4, v0
	v_mul_f32_e32 v4, 0x3fb8aa3b, v0
	v_add_f32_e32 v0, v0, v0
	v_mul_f32_e32 v16, 0x3fb8aa3b, v0
	v_exp_f32_e32 v62, v4
	v_fmamk_f32 v4, v0, 0x3c088889, v189
	v_exp_f32_e32 v16, v16
	v_fmaak_f32 v4, v0, v4, 0x3e2aaaab
	v_fma_f32 v4, v0, v4, 0.5
	v_fma_f32 v4, v0, v4, 1.0
	v_mul_f32_e64 v4, v4, -v0
	v_sub_f32_e32 v16, 1.0, v16
	v_cmp_lt_f32_e32 vcc, s4, v0
	s_nop 1
	v_cndmask_b32_e32 v0, v16, v4, vcc
	v_add_f32_e32 v4, v5, v17
	v_mul_f32_e32 v4, 0xbfb8aa3b, v4
	v_exp_f32_e32 v4, v4
	v_sqrt_f32_e32 v64, v0
	v_add_f32_e32 v0, v21, v37
	v_mul_f32_e32 v0, 0xbfb8aa3b, v0
	v_add_f32_e32 v4, 1.0, v4
	v_rcp_f32_e32 v61, v4
	v_mul_f32_e32 v4, 0xbfb8aa3b, v1
	v_exp_f32_e32 v4, v4
	v_exp_f32_e32 v0, v0
	v_add_f32_e32 v5, 1.0, v4
	v_cmp_gt_f32_e32 vcc, s28, v5
	v_add_f32_e32 v0, 1.0, v0
	v_rcp_f32_e32 v0, v0
	v_cndmask_b32_e64 v16, 0, 32, vcc
	v_ldexp_f32 v5, v5, v16
	v_log_f32_e32 v5, v5
	v_mul_f32_e32 v0, 0xc1000000, v0
	v_mul_f32_e32 v16, 0x3f317217, v5
	v_fma_f32 v16, v5, s0, -v16
	v_fmac_f32_e32 v16, 0x3377d1cf, v5
	v_fmac_f32_e32 v16, 0x3f317217, v5
	v_cmp_lt_f32_e64 s[6:7], |v5|, s1
	s_nop 1
	v_cndmask_b32_e64 v5, v5, v16, s[6:7]
	v_cndmask_b32_e32 v16, 0, v201, vcc
	v_sub_f32_e32 v5, v5, v16
	v_fmamk_f32 v16, v4, 0xbe800000, v188
	v_fma_f32 v16, -v4, v16, 0.5
	v_fma_f32 v16, -v4, v16, 1.0
	v_mul_f32_e32 v16, v4, v16
	v_cmp_gt_f32_e64 s[6:7], s3, v4
	v_cmp_gt_f32_e32 vcc, s2, v1
	s_nop 0
	v_cndmask_b32_e64 v4, v5, v16, s[6:7]
	v_cndmask_b32_e64 v1, v4, -v1, vcc
	v_mul_f32_e32 v0, v0, v1
	v_mul_f32_e32 v1, 0x3fb8aa3b, v0
	v_add_f32_e32 v0, v0, v0
	v_mul_f32_e32 v4, 0x3fb8aa3b, v0
	v_exp_f32_e32 v63, v1
	v_fmamk_f32 v1, v0, 0x3c088889, v189
	v_exp_f32_e32 v4, v4
	v_fmaak_f32 v1, v0, v1, 0x3e2aaaab
	v_fma_f32 v1, v0, v1, 0.5
	v_fma_f32 v1, v0, v1, 1.0
	v_mul_f32_e64 v1, v1, -v0
	v_sub_f32_e32 v4, 1.0, v4
	v_cmp_lt_f32_e32 vcc, s4, v0
	s_nop 1
	v_cndmask_b32_e32 v0, v4, v1, vcc
	v_add_f32_e32 v1, v6, v18
	v_mul_f32_e32 v1, 0xbfb8aa3b, v1
	v_exp_f32_e32 v1, v1
	v_sqrt_f32_e32 v65, v0
	v_add_f32_e32 v0, v22, v38
	v_mul_f32_e32 v0, 0xbfb8aa3b, v0
	v_add_f32_e32 v1, 1.0, v1
	v_rcp_f32_e32 v66, v1
	v_mul_f32_e32 v1, 0xbfb8aa3b, v2
	v_exp_f32_e32 v1, v1
	v_exp_f32_e32 v0, v0
	v_add_f32_e32 v4, 1.0, v1
	v_cmp_gt_f32_e32 vcc, s28, v4
	v_add_f32_e32 v0, 1.0, v0
	v_rcp_f32_e32 v0, v0
	v_cndmask_b32_e64 v5, 0, 32, vcc
	v_ldexp_f32 v4, v4, v5
	v_log_f32_e32 v4, v4
	v_mul_f32_e32 v0, 0xc1000000, v0
	v_mul_f32_e32 v5, 0x3f317217, v4
	v_fma_f32 v5, v4, s0, -v5
	v_fmac_f32_e32 v5, 0x3377d1cf, v4
	v_fmac_f32_e32 v5, 0x3f317217, v4
	v_cmp_lt_f32_e64 s[6:7], |v4|, s1
	s_nop 1
	v_cndmask_b32_e64 v4, v4, v5, s[6:7]
	v_cndmask_b32_e32 v5, 0, v201, vcc
	v_sub_f32_e32 v4, v4, v5
	v_fmamk_f32 v5, v1, 0xbe800000, v188
	v_fma_f32 v5, -v1, v5, 0.5
	v_fma_f32 v5, -v1, v5, 1.0
	v_mul_f32_e32 v5, v1, v5
	v_cmp_gt_f32_e64 s[6:7], s3, v1
	v_cmp_gt_f32_e32 vcc, s2, v2
	s_nop 0
	v_cndmask_b32_e64 v1, v4, v5, s[6:7]
	v_cndmask_b32_e64 v1, v1, -v2, vcc
	v_mul_f32_e32 v0, v0, v1
	v_mul_f32_e32 v1, 0x3fb8aa3b, v0
	v_add_f32_e32 v0, v0, v0
	v_mul_f32_e32 v2, 0x3fb8aa3b, v0
	v_exp_f32_e32 v68, v1
	v_fmamk_f32 v1, v0, 0x3c088889, v189
	v_exp_f32_e32 v2, v2
	v_fmaak_f32 v1, v0, v1, 0x3e2aaaab
	v_fma_f32 v1, v0, v1, 0.5
	v_fma_f32 v1, v0, v1, 1.0
	v_mul_f32_e64 v1, v1, -v0
	v_sub_f32_e32 v2, 1.0, v2
	v_cmp_lt_f32_e32 vcc, s4, v0
	s_nop 1
	v_cndmask_b32_e32 v0, v2, v1, vcc
	v_add_f32_e32 v1, v7, v19
	v_mul_f32_e32 v1, 0xbfb8aa3b, v1
	v_exp_f32_e32 v1, v1
	v_sqrt_f32_e32 v70, v0
	v_add_f32_e32 v0, v23, v39
	v_mul_f32_e32 v0, 0xbfb8aa3b, v0
	v_add_f32_e32 v1, 1.0, v1
	v_rcp_f32_e32 v67, v1
	v_mul_f32_e32 v1, 0xbfb8aa3b, v3
	v_exp_f32_e32 v1, v1
	v_exp_f32_e32 v0, v0
	v_add_f32_e32 v2, 1.0, v1
	v_cmp_gt_f32_e32 vcc, s28, v2
	v_add_f32_e32 v0, 1.0, v0
	v_rcp_f32_e32 v0, v0
	v_cndmask_b32_e64 v4, 0, 32, vcc
	v_ldexp_f32 v2, v2, v4
	v_log_f32_e32 v2, v2
	v_mul_f32_e32 v0, 0xc1000000, v0
	v_mul_f32_e32 v4, 0x3f317217, v2
	v_fma_f32 v4, v2, s0, -v4
	v_fmac_f32_e32 v4, 0x3377d1cf, v2
	v_fmac_f32_e32 v4, 0x3f317217, v2
	v_cmp_lt_f32_e64 s[6:7], |v2|, s1
	s_nop 1
	v_cndmask_b32_e64 v2, v2, v4, s[6:7]
	v_cndmask_b32_e32 v4, 0, v201, vcc
	v_sub_f32_e32 v2, v2, v4
	v_fmamk_f32 v4, v1, 0xbe800000, v188
	v_fma_f32 v4, -v1, v4, 0.5
	v_fma_f32 v4, -v1, v4, 1.0
	v_mul_f32_e32 v4, v1, v4
	v_cmp_gt_f32_e64 s[6:7], s3, v1
	v_cmp_gt_f32_e32 vcc, s2, v3
	s_nop 0
	v_cndmask_b32_e64 v1, v2, v4, s[6:7]
	v_cndmask_b32_e64 v1, v1, -v3, vcc
	v_mul_f32_e32 v0, v0, v1
	v_mul_f32_e32 v1, 0x3fb8aa3b, v0
	v_add_f32_e32 v0, v0, v0
	v_mul_f32_e32 v2, 0x3fb8aa3b, v0
	v_exp_f32_e32 v69, v1
	v_fmamk_f32 v1, v0, 0x3c088889, v189
	v_exp_f32_e32 v2, v2
	v_fmaak_f32 v1, v0, v1, 0x3e2aaaab
	v_fma_f32 v1, v0, v1, 0.5
	v_fma_f32 v1, v0, v1, 1.0
	v_mul_f32_e64 v1, v1, -v0
	v_sub_f32_e32 v2, 1.0, v2
	v_cmp_lt_f32_e32 vcc, s4, v0
	s_nop 1
	v_cndmask_b32_e32 v0, v2, v1, vcc
	v_sqrt_f32_e32 v71, v0
	s_waitcnt vmcnt(0)
	s_nop 7
	v_mov_b32_e32 v0, v170
	v_mov_b32_e32 v1, v171
	v_mov_b32_e32 v2, v172
	v_mov_b32_e32 v3, v173
	v_mov_b32_e32 v4, v144
	v_mov_b32_e32 v5, v145
	v_mov_b32_e32 v6, v166
	v_mov_b32_e32 v7, v167
	v_mov_b32_e32 v16, v180
	v_mov_b32_e32 v17, v181
	v_mov_b32_e32 v18, v202
	v_mov_b32_e32 v19, v203
	global_load_dwordx4 v[170:173], v168, s[10:11] offset:96
	global_load_dwordx2 v[144:145], v168, s[12:13] offset:96
	global_load_dwordx2 v[166:167], v168, s[12:13] offset:104
	global_load_dwordx2 v[180:181], v168, s[8:9] offset:96
	global_load_dwordx2 v[202:203], v168, s[8:9] offset:104
	ds_read_b128 v[36:39], v124 offset:64
	v_add_f32_e32 v0, v24, v0
	v_add_f32_e32 v4, v8, v4
	v_mul_f32_e32 v4, 0xbfb8aa3b, v4
	v_exp_f32_e32 v4, v4
	v_mul_f32_e32 v0, 0xbfb8aa3b, v0
	v_exp_f32_e32 v0, v0
	v_add_f32_e32 v4, 1.0, v4
	v_rcp_f32_e32 v72, v4
	v_mul_f32_e32 v4, 0xbfb8aa3b, v16
	v_exp_f32_e32 v4, v4
	v_add_f32_e32 v0, 1.0, v0
	v_rcp_f32_e32 v0, v0
	v_add_f32_e32 v8, 1.0, v4
	v_cmp_gt_f32_e32 vcc, s28, v8
	v_mul_f32_e32 v0, 0xc1000000, v0
	s_nop 0
	v_cndmask_b32_e64 v20, 0, 32, vcc
	v_ldexp_f32 v8, v8, v20
	v_log_f32_e32 v8, v8
	s_nop 0
	v_mul_f32_e32 v20, 0x3f317217, v8
	v_fma_f32 v20, v8, s0, -v20
	v_fmac_f32_e32 v20, 0x3377d1cf, v8
	v_fmac_f32_e32 v20, 0x3f317217, v8
	v_cmp_lt_f32_e64 s[6:7], |v8|, s1
	s_nop 1
	v_cndmask_b32_e64 v8, v8, v20, s[6:7]
	v_cndmask_b32_e32 v20, 0, v201, vcc
	v_sub_f32_e32 v8, v8, v20
	v_fmamk_f32 v20, v4, 0xbe800000, v188
	v_fma_f32 v20, -v4, v20, 0.5
	v_fma_f32 v20, -v4, v20, 1.0
	v_mul_f32_e32 v20, v4, v20
	v_cmp_gt_f32_e64 s[6:7], s3, v4
	v_cmp_gt_f32_e32 vcc, s2, v16
	s_nop 0
	v_cndmask_b32_e64 v4, v8, v20, s[6:7]
	v_cndmask_b32_e64 v4, v4, -v16, vcc
	v_mul_f32_e32 v0, v0, v4
	v_mul_f32_e32 v4, 0x3fb8aa3b, v0
	v_add_f32_e32 v0, v0, v0
	v_mul_f32_e32 v8, 0x3fb8aa3b, v0
	v_exp_f32_e32 v76, v4
	v_fmamk_f32 v4, v0, 0x3c088889, v189
	v_exp_f32_e32 v8, v8
	v_fmaak_f32 v4, v0, v4, 0x3e2aaaab
	v_fma_f32 v4, v0, v4, 0.5
	v_fma_f32 v4, v0, v4, 1.0
	v_mul_f32_e64 v4, v4, -v0
	v_sub_f32_e32 v8, 1.0, v8
	v_cmp_lt_f32_e32 vcc, s4, v0
	s_nop 1
	v_cndmask_b32_e32 v0, v8, v4, vcc
	v_sqrt_f32_e32 v80, v0
	v_add_f32_e32 v0, v25, v1
	v_add_f32_e32 v1, v9, v5
	v_mul_f32_e32 v1, 0xbfb8aa3b, v1
	v_exp_f32_e32 v1, v1
	v_mul_f32_e32 v0, 0xbfb8aa3b, v0
	v_exp_f32_e32 v0, v0
	v_add_f32_e32 v1, 1.0, v1
	v_rcp_f32_e32 v73, v1
	v_mul_f32_e32 v1, 0xbfb8aa3b, v17
	v_exp_f32_e32 v1, v1
	v_add_f32_e32 v0, 1.0, v0
	v_rcp_f32_e32 v0, v0
	v_add_f32_e32 v4, 1.0, v1
	v_cmp_gt_f32_e32 vcc, s28, v4
	v_mul_f32_e32 v0, 0xc1000000, v0
	s_nop 0
	v_cndmask_b32_e64 v5, 0, 32, vcc
	v_ldexp_f32 v4, v4, v5
	v_log_f32_e32 v4, v4
	s_nop 0
	v_mul_f32_e32 v5, 0x3f317217, v4
	v_fma_f32 v5, v4, s0, -v5
	v_fmac_f32_e32 v5, 0x3377d1cf, v4
	v_fmac_f32_e32 v5, 0x3f317217, v4
	v_cmp_lt_f32_e64 s[6:7], |v4|, s1
	s_nop 1
	v_cndmask_b32_e64 v4, v4, v5, s[6:7]
	v_cndmask_b32_e32 v5, 0, v201, vcc
	v_sub_f32_e32 v4, v4, v5
	v_fmamk_f32 v5, v1, 0xbe800000, v188
	v_fma_f32 v5, -v1, v5, 0.5
	v_fma_f32 v5, -v1, v5, 1.0
	v_mul_f32_e32 v5, v1, v5
	v_cmp_gt_f32_e64 s[6:7], s3, v1
	v_cmp_gt_f32_e32 vcc, s2, v17
	s_nop 0
	v_cndmask_b32_e64 v1, v4, v5, s[6:7]
	v_cndmask_b32_e64 v1, v1, -v17, vcc
	v_mul_f32_e32 v0, v0, v1
	v_mul_f32_e32 v1, 0x3fb8aa3b, v0
	v_add_f32_e32 v0, v0, v0
	v_mul_f32_e32 v4, 0x3fb8aa3b, v0
	v_exp_f32_e32 v77, v1
	v_fmamk_f32 v1, v0, 0x3c088889, v189
	v_exp_f32_e32 v4, v4
	v_fmaak_f32 v1, v0, v1, 0x3e2aaaab
	v_fma_f32 v1, v0, v1, 0.5
	v_fma_f32 v1, v0, v1, 1.0
	v_mul_f32_e64 v1, v1, -v0
	v_sub_f32_e32 v4, 1.0, v4
	v_cmp_lt_f32_e32 vcc, s4, v0
	s_nop 1
	v_cndmask_b32_e32 v0, v4, v1, vcc
	v_add_f32_e32 v1, v10, v6
	v_mul_f32_e32 v1, 0xbfb8aa3b, v1
	v_exp_f32_e32 v1, v1
	v_sqrt_f32_e32 v81, v0
	v_add_f32_e32 v0, v26, v2
	v_mul_f32_e32 v0, 0xbfb8aa3b, v0
	v_add_f32_e32 v1, 1.0, v1
	v_rcp_f32_e32 v74, v1
	v_mul_f32_e32 v1, 0xbfb8aa3b, v18
	v_exp_f32_e32 v1, v1
	v_exp_f32_e32 v0, v0
	v_add_f32_e32 v2, 1.0, v1
	v_cmp_gt_f32_e32 vcc, s28, v2
	v_add_f32_e32 v0, 1.0, v0
	v_rcp_f32_e32 v0, v0
	v_cndmask_b32_e64 v4, 0, 32, vcc
	v_ldexp_f32 v2, v2, v4
	v_log_f32_e32 v2, v2
	v_mul_f32_e32 v0, 0xc1000000, v0
	v_mul_f32_e32 v4, 0x3f317217, v2
	v_fma_f32 v4, v2, s0, -v4
	v_fmac_f32_e32 v4, 0x3377d1cf, v2
	v_fmac_f32_e32 v4, 0x3f317217, v2
	v_cmp_lt_f32_e64 s[6:7], |v2|, s1
	s_nop 1
	v_cndmask_b32_e64 v2, v2, v4, s[6:7]
	v_cndmask_b32_e32 v4, 0, v201, vcc
	v_sub_f32_e32 v2, v2, v4
	v_fmamk_f32 v4, v1, 0xbe800000, v188
	v_fma_f32 v4, -v1, v4, 0.5
	v_fma_f32 v4, -v1, v4, 1.0
	v_mul_f32_e32 v4, v1, v4
	v_cmp_gt_f32_e64 s[6:7], s3, v1
	v_cmp_gt_f32_e32 vcc, s2, v18
	s_nop 0
	v_cndmask_b32_e64 v1, v2, v4, s[6:7]
	v_cndmask_b32_e64 v1, v1, -v18, vcc
	v_mul_f32_e32 v0, v0, v1
	v_mul_f32_e32 v1, 0x3fb8aa3b, v0
	v_add_f32_e32 v0, v0, v0
	v_mul_f32_e32 v2, 0x3fb8aa3b, v0
	v_exp_f32_e32 v78, v1
	v_fmamk_f32 v1, v0, 0x3c088889, v189
	v_exp_f32_e32 v2, v2
	v_fmaak_f32 v1, v0, v1, 0x3e2aaaab
	v_fma_f32 v1, v0, v1, 0.5
	v_fma_f32 v1, v0, v1, 1.0
	v_mul_f32_e64 v1, v1, -v0
	v_sub_f32_e32 v2, 1.0, v2
	v_cmp_lt_f32_e32 vcc, s4, v0
	s_nop 1
	v_cndmask_b32_e32 v0, v2, v1, vcc
	v_add_f32_e32 v1, v11, v7
	v_mul_f32_e32 v1, 0xbfb8aa3b, v1
	v_exp_f32_e32 v1, v1
	v_sqrt_f32_e32 v82, v0
	v_add_f32_e32 v0, v27, v3
	v_mul_f32_e32 v0, 0xbfb8aa3b, v0
	v_add_f32_e32 v1, 1.0, v1
	v_rcp_f32_e32 v75, v1
	v_mul_f32_e32 v1, 0xbfb8aa3b, v19
	v_exp_f32_e32 v1, v1
	v_exp_f32_e32 v0, v0
	v_add_f32_e32 v2, 1.0, v1
	v_cmp_gt_f32_e32 vcc, s28, v2
	v_add_f32_e32 v0, 1.0, v0
	v_rcp_f32_e32 v0, v0
	v_cndmask_b32_e64 v3, 0, 32, vcc
	v_ldexp_f32 v2, v2, v3
	v_log_f32_e32 v2, v2
	v_mul_f32_e32 v0, 0xc1000000, v0
	v_mul_f32_e32 v3, 0x3f317217, v2
	v_fma_f32 v3, v2, s0, -v3
	v_fmac_f32_e32 v3, 0x3377d1cf, v2
	v_fmac_f32_e32 v3, 0x3f317217, v2
	v_cmp_lt_f32_e64 s[6:7], |v2|, s1
	s_nop 1
	v_cndmask_b32_e64 v2, v2, v3, s[6:7]
	v_cndmask_b32_e32 v3, 0, v201, vcc
	v_sub_f32_e32 v2, v2, v3
	v_fmamk_f32 v3, v1, 0xbe800000, v188
	v_fma_f32 v3, -v1, v3, 0.5
	v_fma_f32 v3, -v1, v3, 1.0
	v_mul_f32_e32 v3, v1, v3
	v_cmp_gt_f32_e64 s[6:7], s3, v1
	v_cmp_gt_f32_e32 vcc, s2, v19
	s_nop 0
	v_cndmask_b32_e64 v1, v2, v3, s[6:7]
	v_cndmask_b32_e64 v1, v1, -v19, vcc
	v_mul_f32_e32 v0, v0, v1
	v_mul_f32_e32 v1, 0x3fb8aa3b, v0
	v_add_f32_e32 v0, v0, v0
	v_mul_f32_e32 v2, 0x3fb8aa3b, v0
	v_exp_f32_e32 v79, v1
	v_fmamk_f32 v1, v0, 0x3c088889, v189
	v_exp_f32_e32 v2, v2
	v_fmaak_f32 v1, v0, v1, 0x3e2aaaab
	v_fma_f32 v1, v0, v1, 0.5
	v_fma_f32 v1, v0, v1, 1.0
	v_mul_f32_e64 v1, v1, -v0
	v_sub_f32_e32 v2, 1.0, v2
	v_cmp_lt_f32_e32 vcc, s4, v0
	s_nop 1
	v_cndmask_b32_e32 v0, v2, v1, vcc
	v_sqrt_f32_e32 v83, v0
	s_waitcnt vmcnt(0)
	s_nop 7
	v_mov_b32_e32 v4, v170
	v_mov_b32_e32 v5, v171
	v_mov_b32_e32 v6, v172
	v_mov_b32_e32 v7, v173
	v_mov_b32_e32 v0, v144
	v_mov_b32_e32 v1, v145
	v_mov_b32_e32 v2, v166
	v_mov_b32_e32 v3, v167
	v_mov_b32_e32 v8, v180
	v_mov_b32_e32 v9, v181
	v_mov_b32_e32 v10, v202
	v_mov_b32_e32 v11, v203
	global_load_dwordx4 v[170:173], v168, s[10:11] offset:128
	global_load_dwordx2 v[144:145], v168, s[12:13] offset:128
	global_load_dwordx2 v[166:167], v168, s[12:13] offset:136
	global_load_dwordx2 v[180:181], v168, s[8:9] offset:128
	global_load_dwordx2 v[202:203], v168, s[8:9] offset:136
	ds_read_b128 v[40:43], v124 offset:96
	v_add_f32_e32 v4, v28, v4
	v_mul_f32_e32 v4, 0xbfb8aa3b, v4
	v_exp_f32_e32 v4, v4
	v_add_f32_e32 v0, v12, v0
	v_mul_f32_e32 v0, 0xbfb8aa3b, v0
	v_exp_f32_e32 v0, v0
	v_add_f32_e32 v4, 1.0, v4
	v_rcp_f32_e32 v4, v4
	v_add_f32_e32 v1, v13, v1
	v_add_f32_e32 v0, 1.0, v0
	v_rcp_f32_e32 v84, v0
	v_mul_f32_e32 v0, 0xc1000000, v4
	v_mul_f32_e32 v4, 0xbfb8aa3b, v8
	v_exp_f32_e32 v4, v4
	v_mul_f32_e32 v1, 0xbfb8aa3b, v1
	v_exp_f32_e32 v1, v1
	v_add_f32_e32 v12, 1.0, v4
	v_cmp_gt_f32_e32 vcc, s28, v12
	v_add_f32_e32 v1, 1.0, v1
	v_rcp_f32_e32 v85, v1
	v_cndmask_b32_e64 v16, 0, 32, vcc
	v_ldexp_f32 v12, v12, v16
	v_log_f32_e32 v12, v12
	v_mul_f32_e32 v1, 0xbfb8aa3b, v9
	v_exp_f32_e32 v1, v1
	v_mul_f32_e32 v16, 0x3f317217, v12
	v_fma_f32 v16, v12, s0, -v16
	v_fmac_f32_e32 v16, 0x3377d1cf, v12
	v_fmac_f32_e32 v16, 0x3f317217, v12
	v_cmp_lt_f32_e64 s[6:7], |v12|, s1
	s_nop 1
	v_cndmask_b32_e64 v12, v12, v16, s[6:7]
	v_cndmask_b32_e32 v16, 0, v201, vcc
	v_sub_f32_e32 v12, v12, v16
	v_fmamk_f32 v16, v4, 0xbe800000, v188
	v_fma_f32 v16, -v4, v16, 0.5
	v_fma_f32 v16, -v4, v16, 1.0
	v_mul_f32_e32 v16, v4, v16
	v_cmp_gt_f32_e64 s[6:7], s3, v4
	v_cmp_gt_f32_e32 vcc, s2, v8
	s_nop 0
	v_cndmask_b32_e64 v4, v12, v16, s[6:7]
	v_cndmask_b32_e64 v4, v4, -v8, vcc
	v_mul_f32_e32 v0, v0, v4
	v_mul_f32_e32 v4, 0x3fb8aa3b, v0
	v_add_f32_e32 v0, v0, v0
	v_mul_f32_e32 v8, 0x3fb8aa3b, v0
	v_exp_f32_e32 v86, v4
	v_fmamk_f32 v4, v0, 0x3c088889, v189
	v_exp_f32_e32 v8, v8
	v_fmaak_f32 v4, v0, v4, 0x3e2aaaab
	v_fma_f32 v4, v0, v4, 0.5
	v_fma_f32 v4, v0, v4, 1.0
	v_mul_f32_e64 v4, v4, -v0
	v_sub_f32_e32 v8, 1.0, v8
	v_cmp_lt_f32_e32 vcc, s4, v0
	s_nop 1
	v_cndmask_b32_e32 v0, v8, v4, vcc
	v_add_f32_e32 v4, 1.0, v1
	v_cmp_gt_f32_e32 vcc, s28, v4
	v_sqrt_f32_e32 v88, v0
	v_add_f32_e32 v0, v29, v5
	v_cndmask_b32_e64 v5, 0, 32, vcc
	v_ldexp_f32 v4, v4, v5
	v_log_f32_e32 v4, v4
	v_mul_f32_e32 v0, 0xbfb8aa3b, v0
	v_exp_f32_e32 v0, v0
	v_mul_f32_e32 v5, 0x3f317217, v4
	v_fma_f32 v5, v4, s0, -v5
	v_fmac_f32_e32 v5, 0x3377d1cf, v4
	v_fmac_f32_e32 v5, 0x3f317217, v4
	v_cmp_lt_f32_e64 s[6:7], |v4|, s1
	v_add_f32_e32 v0, 1.0, v0
	v_rcp_f32_e32 v0, v0
	v_cndmask_b32_e64 v4, v4, v5, s[6:7]
	v_cndmask_b32_e32 v5, 0, v201, vcc
	v_sub_f32_e32 v4, v4, v5
	v_fmamk_f32 v5, v1, 0xbe800000, v188
	v_fma_f32 v5, -v1, v5, 0.5
	v_fma_f32 v5, -v1, v5, 1.0
	v_mul_f32_e32 v5, v1, v5
	v_cmp_gt_f32_e64 s[6:7], s3, v1
	v_cmp_gt_f32_e32 vcc, s2, v9
	v_mul_f32_e32 v0, 0xc1000000, v0
	v_cndmask_b32_e64 v1, v4, v5, s[6:7]
	v_cndmask_b32_e64 v1, v1, -v9, vcc
	v_mul_f32_e32 v0, v0, v1
	v_mul_f32_e32 v1, 0x3fb8aa3b, v0
	v_add_f32_e32 v0, v0, v0
	v_mul_f32_e32 v4, 0x3fb8aa3b, v0
	v_exp_f32_e32 v87, v1
	v_fmamk_f32 v1, v0, 0x3c088889, v189
	v_exp_f32_e32 v4, v4
	v_fmaak_f32 v1, v0, v1, 0x3e2aaaab
	v_fma_f32 v1, v0, v1, 0.5
	v_fma_f32 v1, v0, v1, 1.0
	v_mul_f32_e64 v1, v1, -v0
	v_sub_f32_e32 v4, 1.0, v4
	v_cmp_lt_f32_e32 vcc, s4, v0
	s_nop 1
	v_cndmask_b32_e32 v0, v4, v1, vcc
	v_add_f32_e32 v1, v14, v2
	v_mul_f32_e32 v1, 0xbfb8aa3b, v1
	v_exp_f32_e32 v1, v1
	v_sqrt_f32_e32 v89, v0
	v_add_f32_e32 v0, v30, v6
	v_mul_f32_e32 v0, 0xbfb8aa3b, v0
	v_add_f32_e32 v1, 1.0, v1
	v_rcp_f32_e32 v90, v1
	v_mul_f32_e32 v1, 0xbfb8aa3b, v10
	v_exp_f32_e32 v1, v1
	v_exp_f32_e32 v0, v0
	v_add_f32_e32 v2, 1.0, v1
	v_cmp_gt_f32_e32 vcc, s28, v2
	v_add_f32_e32 v0, 1.0, v0
	v_rcp_f32_e32 v0, v0
	v_cndmask_b32_e64 v4, 0, 32, vcc
	v_ldexp_f32 v2, v2, v4
	v_log_f32_e32 v2, v2
	v_mul_f32_e32 v0, 0xc1000000, v0
	v_mul_f32_e32 v4, 0x3f317217, v2
	v_fma_f32 v4, v2, s0, -v4
	v_fmac_f32_e32 v4, 0x3377d1cf, v2
	v_fmac_f32_e32 v4, 0x3f317217, v2
	v_cmp_lt_f32_e64 s[6:7], |v2|, s1
	s_nop 1
	v_cndmask_b32_e64 v2, v2, v4, s[6:7]
	v_cndmask_b32_e32 v4, 0, v201, vcc
	v_sub_f32_e32 v2, v2, v4
	v_fmamk_f32 v4, v1, 0xbe800000, v188
	v_fma_f32 v4, -v1, v4, 0.5
	v_fma_f32 v4, -v1, v4, 1.0
	v_mul_f32_e32 v4, v1, v4
	v_cmp_gt_f32_e64 s[6:7], s3, v1
	v_cmp_gt_f32_e32 vcc, s2, v10
	s_nop 0
	v_cndmask_b32_e64 v1, v2, v4, s[6:7]
	v_cndmask_b32_e64 v1, v1, -v10, vcc
	v_mul_f32_e32 v0, v0, v1
	v_mul_f32_e32 v1, 0x3fb8aa3b, v0
	v_add_f32_e32 v0, v0, v0
	v_mul_f32_e32 v2, 0x3fb8aa3b, v0
	v_exp_f32_e32 v92, v1
	v_fmamk_f32 v1, v0, 0x3c088889, v189
	v_exp_f32_e32 v2, v2
	v_fmaak_f32 v1, v0, v1, 0x3e2aaaab
	v_fma_f32 v1, v0, v1, 0.5
	v_fma_f32 v1, v0, v1, 1.0
	v_mul_f32_e64 v1, v1, -v0
	v_sub_f32_e32 v2, 1.0, v2
	v_cmp_lt_f32_e32 vcc, s4, v0
	s_nop 1
	v_cndmask_b32_e32 v0, v2, v1, vcc
	v_add_f32_e32 v1, v15, v3
	v_mul_f32_e32 v1, 0xbfb8aa3b, v1
	v_exp_f32_e32 v1, v1
	v_sqrt_f32_e32 v94, v0
	v_add_f32_e32 v0, v31, v7
	v_mul_f32_e32 v0, 0xbfb8aa3b, v0
	v_add_f32_e32 v1, 1.0, v1
	v_rcp_f32_e32 v91, v1
	v_mul_f32_e32 v1, 0xbfb8aa3b, v11
	v_exp_f32_e32 v1, v1
	v_exp_f32_e32 v0, v0
	v_add_f32_e32 v2, 1.0, v1
	v_cmp_gt_f32_e32 vcc, s28, v2
	v_add_f32_e32 v0, 1.0, v0
	v_rcp_f32_e32 v0, v0
	v_cndmask_b32_e64 v3, 0, 32, vcc
	v_ldexp_f32 v2, v2, v3
	v_log_f32_e32 v2, v2
	v_mul_f32_e32 v0, 0xc1000000, v0
	v_mul_f32_e32 v3, 0x3f317217, v2
	v_fma_f32 v3, v2, s0, -v3
	v_fmac_f32_e32 v3, 0x3377d1cf, v2
	v_fmac_f32_e32 v3, 0x3f317217, v2
	v_cmp_lt_f32_e64 s[6:7], |v2|, s1
	s_nop 1
	v_cndmask_b32_e64 v2, v2, v3, s[6:7]
	v_cndmask_b32_e32 v3, 0, v201, vcc
	v_sub_f32_e32 v2, v2, v3
	v_fmamk_f32 v3, v1, 0xbe800000, v188
	v_fma_f32 v3, -v1, v3, 0.5
	v_fma_f32 v3, -v1, v3, 1.0
	v_mul_f32_e32 v3, v1, v3
	v_cmp_gt_f32_e64 s[6:7], s3, v1
	v_cmp_gt_f32_e32 vcc, s2, v11
	s_nop 0
	v_cndmask_b32_e64 v1, v2, v3, s[6:7]
	v_cndmask_b32_e64 v1, v1, -v11, vcc
	v_mul_f32_e32 v0, v0, v1
	v_mul_f32_e32 v1, 0x3fb8aa3b, v0
	v_add_f32_e32 v0, v0, v0
	v_mul_f32_e32 v2, 0x3fb8aa3b, v0
	v_exp_f32_e32 v93, v1
	v_fmamk_f32 v1, v0, 0x3c088889, v189
	v_exp_f32_e32 v2, v2
	v_fmaak_f32 v1, v0, v1, 0x3e2aaaab
	v_fma_f32 v1, v0, v1, 0.5
	v_fma_f32 v1, v0, v1, 1.0
	v_mul_f32_e64 v1, v1, -v0
	v_sub_f32_e32 v2, 1.0, v2
	v_cmp_lt_f32_e32 vcc, s4, v0
	s_nop 1
	v_cndmask_b32_e32 v0, v2, v1, vcc
	v_sqrt_f32_e32 v95, v0
	v_or_b32_e32 v0, 0x1000, v100
	v_mov_b32_e32 v1, v169
	v_lshl_add_u64 v[100:101], v[96:97], 0, v[0:1]
	v_lshl_add_u64 v[102:103], v[98:99], 0, v[0:1]
	global_load_dwordx4 v[0:3], v[100:101], off
	global_load_dwordx4 v[4:7], v[102:103], off
	s_waitcnt vmcnt(1)
	v_mfma_f32_32x32x16_bf16 v[16:31], v[0:3], v[56:59], 0
	s_waitcnt vmcnt(0)
	v_mfma_f32_32x32x16_bf16 v[0:15], v[4:7], v[56:59], 0
	global_load_dwordx4 v[56:59], v[100:101], off offset:32
	global_load_dwordx4 v[96:99], v[102:103], off offset:32
	s_waitcnt vmcnt(1)
	v_mfma_f32_32x32x16_bf16 v[16:31], v[56:59], v[52:55], v[16:31]
	s_waitcnt vmcnt(0)
	v_mfma_f32_32x32x16_bf16 v[0:15], v[96:99], v[52:55], v[0:15]
	global_load_dwordx4 v[52:55], v[100:101], off offset:64
	global_load_dwordx4 v[56:59], v[102:103], off offset:64
	s_waitcnt vmcnt(1)
	v_mfma_f32_32x32x16_bf16 v[16:31], v[52:55], v[48:51], v[16:31]
	s_waitcnt vmcnt(0)
	v_mfma_f32_32x32x16_bf16 v[0:15], v[56:59], v[48:51], v[0:15]
	global_load_dwordx4 v[48:51], v[100:101], off offset:96
	global_load_dwordx4 v[52:55], v[102:103], off offset:96
	s_waitcnt vmcnt(0)
	v_mfma_f32_32x32x16_bf16 v[0:15], v[52:55], v[44:47], v[0:15]
	s_waitcnt vmcnt(0)
	s_nop 7
	v_mov_b32_e32 v52, v170
	v_mov_b32_e32 v53, v171
	v_mov_b32_e32 v54, v172
	v_mov_b32_e32 v55, v173
	v_mov_b32_e32 v56, v144
	v_mov_b32_e32 v57, v145
	v_mov_b32_e32 v58, v166
	v_mov_b32_e32 v59, v167
	v_mov_b32_e32 v96, v180
	v_mov_b32_e32 v97, v181
	v_mov_b32_e32 v98, v202
	v_mov_b32_e32 v99, v203
	global_load_dwordx4 v[170:173], v168, s[10:11] offset:160
	global_load_dwordx2 v[144:145], v168, s[12:13] offset:160
	global_load_dwordx2 v[166:167], v168, s[12:13] offset:168
	global_load_dwordx2 v[180:181], v168, s[8:9] offset:160
	global_load_dwordx2 v[202:203], v168, s[8:9] offset:168
	s_nop 7
	v_add_f32_e32 v0, v0, v56
	v_mfma_f32_32x32x16_bf16 v[16:31], v[48:51], v[44:47], v[16:31]
	v_mul_f32_e32 v0, 0xbfb8aa3b, v0
	v_exp_f32_e32 v0, v0
	v_add_f32_e32 v1, v1, v57
	v_mul_f32_e32 v1, 0xbfb8aa3b, v1
	v_exp_f32_e32 v1, v1
	v_add_f32_e32 v0, 1.0, v0
	v_rcp_f32_e32 v56, v0
	s_nop 4
	v_add_f32_e32 v16, v16, v52
	v_mul_f32_e32 v16, 0xbfb8aa3b, v16
	v_exp_f32_e32 v16, v16
	v_add_f32_e32 v1, 1.0, v1
	v_rcp_f32_e32 v57, v1
	v_mul_f32_e32 v1, 0xbfb8aa3b, v97
	v_add_f32_e32 v16, 1.0, v16
	v_rcp_f32_e32 v16, v16
	v_exp_f32_e32 v1, v1
	ds_read_b128 v[48:51], v124 offset:128
	ds_read_b128 v[44:47], v124 offset:160
	v_mul_f32_e32 v0, 0xc1000000, v16
	v_mul_f32_e32 v16, 0xbfb8aa3b, v96
	v_exp_f32_e32 v16, v16
	s_nop 0
	v_add_f32_e32 v52, 1.0, v16
	v_cmp_gt_f32_e32 vcc, s28, v52
	s_nop 1
	v_cndmask_b32_e64 v100, 0, 32, vcc
	v_ldexp_f32 v52, v52, v100
	v_log_f32_e32 v52, v52
	s_nop 0
	v_mul_f32_e32 v100, 0x3f317217, v52
	v_fma_f32 v100, v52, s0, -v100
	v_fmac_f32_e32 v100, 0x3377d1cf, v52
	v_fmac_f32_e32 v100, 0x3f317217, v52
	v_cmp_lt_f32_e64 s[6:7], |v52|, s1
	s_nop 1
	v_cndmask_b32_e64 v52, v52, v100, s[6:7]
	v_cndmask_b32_e32 v100, 0, v201, vcc
	v_sub_f32_e32 v52, v52, v100
	v_fmamk_f32 v100, v16, 0xbe800000, v188
	v_fma_f32 v100, -v16, v100, 0.5
	v_fma_f32 v100, -v16, v100, 1.0
	v_mul_f32_e32 v100, v16, v100
	v_cmp_gt_f32_e64 s[6:7], s3, v16
	v_cmp_gt_f32_e32 vcc, s2, v96
	s_nop 0
	v_cndmask_b32_e64 v16, v52, v100, s[6:7]
	v_cndmask_b32_e64 v16, v16, -v96, vcc
	v_mul_f32_e32 v0, v0, v16
	v_mul_f32_e32 v16, 0x3fb8aa3b, v0
	v_add_f32_e32 v0, v0, v0
	v_mul_f32_e32 v52, 0x3fb8aa3b, v0
	v_exp_f32_e32 v96, v16
	v_fmamk_f32 v16, v0, 0x3c088889, v189
	v_exp_f32_e32 v52, v52
	v_fmaak_f32 v16, v0, v16, 0x3e2aaaab
	v_fma_f32 v16, v0, v16, 0.5
	v_fma_f32 v16, v0, v16, 1.0
	v_mul_f32_e64 v16, v16, -v0
	v_sub_f32_e32 v52, 1.0, v52
	v_cmp_lt_f32_e32 vcc, s4, v0
	s_nop 1
	v_cndmask_b32_e32 v0, v52, v16, vcc
	v_add_f32_e32 v16, 1.0, v1
	v_cmp_gt_f32_e32 vcc, s28, v16
	v_sqrt_f32_e32 v100, v0
	v_add_f32_e32 v0, v17, v53
	v_cndmask_b32_e64 v17, 0, 32, vcc
	v_ldexp_f32 v16, v16, v17
	v_log_f32_e32 v16, v16
	v_mul_f32_e32 v0, 0xbfb8aa3b, v0
	v_exp_f32_e32 v0, v0
	v_mul_f32_e32 v17, 0x3f317217, v16
	v_fma_f32 v17, v16, s0, -v17
	v_fmac_f32_e32 v17, 0x3377d1cf, v16
	v_fmac_f32_e32 v17, 0x3f317217, v16
	v_cmp_lt_f32_e64 s[6:7], |v16|, s1
	v_add_f32_e32 v0, 1.0, v0
	v_rcp_f32_e32 v0, v0
	v_cndmask_b32_e64 v16, v16, v17, s[6:7]
	v_cndmask_b32_e32 v17, 0, v201, vcc
	v_sub_f32_e32 v16, v16, v17
	v_fmamk_f32 v17, v1, 0xbe800000, v188
	v_fma_f32 v17, -v1, v17, 0.5
	v_fma_f32 v17, -v1, v17, 1.0
	v_mul_f32_e32 v17, v1, v17
	v_cmp_gt_f32_e64 s[6:7], s3, v1
	v_cmp_gt_f32_e32 vcc, s2, v97
	v_mul_f32_e32 v0, 0xc1000000, v0
	v_cndmask_b32_e64 v1, v16, v17, s[6:7]
	v_cndmask_b32_e64 v1, v1, -v97, vcc
	v_mul_f32_e32 v0, v0, v1
	v_mul_f32_e32 v1, 0x3fb8aa3b, v0
	v_add_f32_e32 v0, v0, v0
	v_mul_f32_e32 v16, 0x3fb8aa3b, v0
	v_exp_f32_e32 v97, v1
	v_fmamk_f32 v1, v0, 0x3c088889, v189
	v_exp_f32_e32 v16, v16
	v_fmaak_f32 v1, v0, v1, 0x3e2aaaab
	v_fma_f32 v1, v0, v1, 0.5
	v_fma_f32 v1, v0, v1, 1.0
	v_mul_f32_e64 v1, v1, -v0
	v_sub_f32_e32 v16, 1.0, v16
	v_cmp_lt_f32_e32 vcc, s4, v0
	s_nop 1
	v_cndmask_b32_e32 v0, v16, v1, vcc
	v_add_f32_e32 v1, v2, v58
	v_mul_f32_e32 v1, 0xbfb8aa3b, v1
	v_exp_f32_e32 v1, v1
	v_sqrt_f32_e32 v101, v0
	v_add_f32_e32 v0, v18, v54
	v_mul_f32_e32 v0, 0xbfb8aa3b, v0
	v_add_f32_e32 v1, 1.0, v1
	v_rcp_f32_e32 v58, v1
	v_mul_f32_e32 v1, 0xbfb8aa3b, v98
	v_exp_f32_e32 v1, v1
	v_exp_f32_e32 v0, v0
	v_add_f32_e32 v2, 1.0, v1
	v_cmp_gt_f32_e32 vcc, s28, v2
	v_add_f32_e32 v0, 1.0, v0
	v_rcp_f32_e32 v0, v0
	v_cndmask_b32_e64 v16, 0, 32, vcc
	v_ldexp_f32 v2, v2, v16
	v_log_f32_e32 v2, v2
	v_mul_f32_e32 v0, 0xc1000000, v0
	v_mul_f32_e32 v16, 0x3f317217, v2
	v_fma_f32 v16, v2, s0, -v16
	v_fmac_f32_e32 v16, 0x3377d1cf, v2
	v_fmac_f32_e32 v16, 0x3f317217, v2
	v_cmp_lt_f32_e64 s[6:7], |v2|, s1
	s_nop 1
	v_cndmask_b32_e64 v2, v2, v16, s[6:7]
	v_cndmask_b32_e32 v16, 0, v201, vcc
	v_sub_f32_e32 v2, v2, v16
	v_fmamk_f32 v16, v1, 0xbe800000, v188
	v_fma_f32 v16, -v1, v16, 0.5
	v_fma_f32 v16, -v1, v16, 1.0
	v_mul_f32_e32 v16, v1, v16
	v_cmp_gt_f32_e64 s[6:7], s3, v1
	v_cmp_gt_f32_e32 vcc, s2, v98
	s_nop 0
	v_cndmask_b32_e64 v1, v2, v16, s[6:7]
	v_cndmask_b32_e64 v1, v1, -v98, vcc
	v_mul_f32_e32 v0, v0, v1
	v_mul_f32_e32 v1, 0x3fb8aa3b, v0
	v_add_f32_e32 v0, v0, v0
	v_mul_f32_e32 v2, 0x3fb8aa3b, v0
	v_exp_f32_e32 v98, v1
	v_fmamk_f32 v1, v0, 0x3c088889, v189
	v_exp_f32_e32 v2, v2
	v_fmaak_f32 v1, v0, v1, 0x3e2aaaab
	v_fma_f32 v1, v0, v1, 0.5
	v_fma_f32 v1, v0, v1, 1.0
	v_mul_f32_e64 v1, v1, -v0
	v_sub_f32_e32 v2, 1.0, v2
	v_cmp_lt_f32_e32 vcc, s4, v0
	s_nop 1
	v_cndmask_b32_e32 v0, v2, v1, vcc
	v_add_f32_e32 v1, v3, v59
	v_mul_f32_e32 v1, 0xbfb8aa3b, v1
	v_exp_f32_e32 v1, v1
	v_sqrt_f32_e32 v102, v0
	v_add_f32_e32 v0, v19, v55
	v_mul_f32_e32 v0, 0xbfb8aa3b, v0
	v_add_f32_e32 v1, 1.0, v1
	v_rcp_f32_e32 v59, v1
	v_mul_f32_e32 v1, 0xbfb8aa3b, v99
	v_exp_f32_e32 v1, v1
	v_exp_f32_e32 v0, v0
	v_add_f32_e32 v2, 1.0, v1
	v_cmp_gt_f32_e32 vcc, s28, v2
	v_add_f32_e32 v0, 1.0, v0
	v_rcp_f32_e32 v0, v0
	v_cndmask_b32_e64 v3, 0, 32, vcc
	v_ldexp_f32 v2, v2, v3
	v_log_f32_e32 v2, v2
	v_mul_f32_e32 v0, 0xc1000000, v0
	v_mul_f32_e32 v3, 0x3f317217, v2
	v_fma_f32 v3, v2, s0, -v3
	v_fmac_f32_e32 v3, 0x3377d1cf, v2
	v_fmac_f32_e32 v3, 0x3f317217, v2
	v_cmp_lt_f32_e64 s[6:7], |v2|, s1
	s_nop 1
	v_cndmask_b32_e64 v2, v2, v3, s[6:7]
	v_cndmask_b32_e32 v3, 0, v201, vcc
	v_sub_f32_e32 v2, v2, v3
	v_fmamk_f32 v3, v1, 0xbe800000, v188
	v_fma_f32 v3, -v1, v3, 0.5
	v_fma_f32 v3, -v1, v3, 1.0
	v_mul_f32_e32 v3, v1, v3
	v_cmp_gt_f32_e64 s[6:7], s3, v1
	v_cmp_gt_f32_e32 vcc, s2, v99
	s_nop 0
	v_cndmask_b32_e64 v1, v2, v3, s[6:7]
	v_cndmask_b32_e64 v1, v1, -v99, vcc
	v_mul_f32_e32 v0, v0, v1
	v_mul_f32_e32 v1, 0x3fb8aa3b, v0
	v_add_f32_e32 v0, v0, v0
	v_mul_f32_e32 v2, 0x3fb8aa3b, v0
	v_exp_f32_e32 v99, v1
	v_fmamk_f32 v1, v0, 0x3c088889, v189
	v_exp_f32_e32 v2, v2
	v_fmaak_f32 v1, v0, v1, 0x3e2aaaab
	v_fma_f32 v1, v0, v1, 0.5
	v_fma_f32 v1, v0, v1, 1.0
	v_mul_f32_e64 v1, v1, -v0
	v_sub_f32_e32 v2, 1.0, v2
	v_cmp_lt_f32_e32 vcc, s4, v0
	s_nop 1
	v_cndmask_b32_e32 v0, v2, v1, vcc
	v_sqrt_f32_e32 v103, v0
	s_waitcnt vmcnt(0)
	s_nop 7
	v_mov_b32_e32 v16, v170
	v_mov_b32_e32 v17, v171
	v_mov_b32_e32 v18, v172
	v_mov_b32_e32 v19, v173
	v_mov_b32_e32 v0, v144
	v_mov_b32_e32 v1, v145
	v_mov_b32_e32 v2, v166
	v_mov_b32_e32 v3, v167
	v_mov_b32_e32 v52, v180
	v_mov_b32_e32 v53, v181
	v_mov_b32_e32 v54, v202
	v_mov_b32_e32 v55, v203
	global_load_dwordx4 v[170:173], v168, s[10:11] offset:192
	global_load_dwordx2 v[144:145], v168, s[12:13] offset:192
	global_load_dwordx2 v[166:167], v168, s[12:13] offset:200
	global_load_dwordx2 v[180:181], v168, s[8:9] offset:192
	global_load_dwordx2 v[202:203], v168, s[8:9] offset:200
	v_add_f32_e32 v16, v20, v16
	v_mul_f32_e32 v16, 0xbfb8aa3b, v16
	v_exp_f32_e32 v16, v16
	v_add_f32_e32 v0, v4, v0
	v_mul_f32_e32 v0, 0xbfb8aa3b, v0
	v_exp_f32_e32 v0, v0
	v_add_f32_e32 v16, 1.0, v16
	v_mul_f32_e32 v4, 0xbfb8aa3b, v52
	v_rcp_f32_e32 v16, v16
	v_exp_f32_e32 v4, v4
	v_add_f32_e32 v0, 1.0, v0
	v_rcp_f32_e32 v104, v0
	v_mul_f32_e32 v0, 0xc1000000, v16
	v_add_f32_e32 v16, 1.0, v4
	v_cmp_gt_f32_e32 vcc, s28, v16
	v_add_f32_e32 v1, v5, v1
	v_mul_f32_e32 v1, 0xbfb8aa3b, v1
	v_cndmask_b32_e64 v20, 0, 32, vcc
	v_ldexp_f32 v16, v16, v20
	v_log_f32_e32 v16, v16
	v_exp_f32_e32 v1, v1
	v_mul_f32_e32 v20, 0x3f317217, v16
	v_fma_f32 v20, v16, s0, -v20
	v_fmac_f32_e32 v20, 0x3377d1cf, v16
	v_fmac_f32_e32 v20, 0x3f317217, v16
	v_cmp_lt_f32_e64 s[6:7], |v16|, s1
	v_add_f32_e32 v1, 1.0, v1
	v_rcp_f32_e32 v105, v1
	v_cndmask_b32_e64 v16, v16, v20, s[6:7]
	v_cndmask_b32_e32 v20, 0, v201, vcc
	v_sub_f32_e32 v16, v16, v20
	v_fmamk_f32 v20, v4, 0xbe800000, v188
	v_fma_f32 v20, -v4, v20, 0.5
	v_fma_f32 v20, -v4, v20, 1.0
	v_mul_f32_e32 v20, v4, v20
	v_cmp_gt_f32_e64 s[6:7], s3, v4
	v_cmp_gt_f32_e32 vcc, s2, v52
	v_mul_f32_e32 v1, 0xbfb8aa3b, v53
	v_cndmask_b32_e64 v4, v16, v20, s[6:7]
	v_cndmask_b32_e64 v4, v4, -v52, vcc
	v_mul_f32_e32 v0, v0, v4
	v_mul_f32_e32 v4, 0x3fb8aa3b, v0
	v_add_f32_e32 v0, v0, v0
	v_mul_f32_e32 v16, 0x3fb8aa3b, v0
	v_exp_f32_e32 v52, v4
	v_fmamk_f32 v4, v0, 0x3c088889, v189
	v_exp_f32_e32 v16, v16
	v_fmaak_f32 v4, v0, v4, 0x3e2aaaab
	v_exp_f32_e32 v1, v1
	v_fma_f32 v4, v0, v4, 0.5
	v_fma_f32 v4, v0, v4, 1.0
	v_mul_f32_e64 v4, v4, -v0
	v_sub_f32_e32 v16, 1.0, v16
	v_cmp_lt_f32_e32 vcc, s4, v0
	s_nop 1
	v_cndmask_b32_e32 v0, v16, v4, vcc
	v_add_f32_e32 v4, 1.0, v1
	v_cmp_gt_f32_e32 vcc, s28, v4
	v_sqrt_f32_e32 v106, v0
	v_add_f32_e32 v0, v21, v17
	v_cndmask_b32_e64 v5, 0, 32, vcc
	v_ldexp_f32 v4, v4, v5
	v_log_f32_e32 v4, v4
	v_mul_f32_e32 v0, 0xbfb8aa3b, v0
	v_exp_f32_e32 v0, v0
	v_mul_f32_e32 v5, 0x3f317217, v4
	v_fma_f32 v5, v4, s0, -v5
	v_fmac_f32_e32 v5, 0x3377d1cf, v4
	v_fmac_f32_e32 v5, 0x3f317217, v4
	v_cmp_lt_f32_e64 s[6:7], |v4|, s1
	v_add_f32_e32 v0, 1.0, v0
	v_rcp_f32_e32 v0, v0
	v_cndmask_b32_e64 v4, v4, v5, s[6:7]
	v_cndmask_b32_e32 v5, 0, v201, vcc
	v_sub_f32_e32 v4, v4, v5
	v_fmamk_f32 v5, v1, 0xbe800000, v188
	v_fma_f32 v5, -v1, v5, 0.5
	v_fma_f32 v5, -v1, v5, 1.0
	v_mul_f32_e32 v5, v1, v5
	v_cmp_gt_f32_e64 s[6:7], s3, v1
	v_cmp_gt_f32_e32 vcc, s2, v53
	v_mul_f32_e32 v0, 0xc1000000, v0
	v_cndmask_b32_e64 v1, v4, v5, s[6:7]
	v_cndmask_b32_e64 v1, v1, -v53, vcc
	v_mul_f32_e32 v0, v0, v1
	v_mul_f32_e32 v1, 0x3fb8aa3b, v0
	v_add_f32_e32 v0, v0, v0
	v_mul_f32_e32 v4, 0x3fb8aa3b, v0
	v_exp_f32_e32 v53, v1
	v_fmamk_f32 v1, v0, 0x3c088889, v189
	v_exp_f32_e32 v4, v4
	v_fmaak_f32 v1, v0, v1, 0x3e2aaaab
	v_fma_f32 v1, v0, v1, 0.5
	v_fma_f32 v1, v0, v1, 1.0
	v_mul_f32_e64 v1, v1, -v0
	v_sub_f32_e32 v4, 1.0, v4
	v_cmp_lt_f32_e32 vcc, s4, v0
	s_nop 1
	v_cndmask_b32_e32 v0, v4, v1, vcc
	v_add_f32_e32 v1, v6, v2
	v_mul_f32_e32 v1, 0xbfb8aa3b, v1
	v_exp_f32_e32 v1, v1
	v_sqrt_f32_e32 v107, v0
	v_add_f32_e32 v0, v22, v18
	v_mul_f32_e32 v0, 0xbfb8aa3b, v0
	v_add_f32_e32 v1, 1.0, v1
	v_rcp_f32_e32 v108, v1
	v_mul_f32_e32 v1, 0xbfb8aa3b, v54
	v_exp_f32_e32 v1, v1
	v_exp_f32_e32 v0, v0
	v_add_f32_e32 v2, 1.0, v1
	v_cmp_gt_f32_e32 vcc, s28, v2
	v_add_f32_e32 v0, 1.0, v0
	v_rcp_f32_e32 v0, v0
	v_cndmask_b32_e64 v4, 0, 32, vcc
	v_ldexp_f32 v2, v2, v4
	v_log_f32_e32 v2, v2
	v_mul_f32_e32 v0, 0xc1000000, v0
	v_mul_f32_e32 v4, 0x3f317217, v2
	v_fma_f32 v4, v2, s0, -v4
	v_fmac_f32_e32 v4, 0x3377d1cf, v2
	v_fmac_f32_e32 v4, 0x3f317217, v2
	v_cmp_lt_f32_e64 s[6:7], |v2|, s1
	s_nop 1
	v_cndmask_b32_e64 v2, v2, v4, s[6:7]
	v_cndmask_b32_e32 v4, 0, v201, vcc
	v_sub_f32_e32 v2, v2, v4
	v_fmamk_f32 v4, v1, 0xbe800000, v188
	v_fma_f32 v4, -v1, v4, 0.5
	v_fma_f32 v4, -v1, v4, 1.0
	v_mul_f32_e32 v4, v1, v4
	v_cmp_gt_f32_e64 s[6:7], s3, v1
	v_cmp_gt_f32_e32 vcc, s2, v54
	s_nop 0
	v_cndmask_b32_e64 v1, v2, v4, s[6:7]
	v_cndmask_b32_e64 v1, v1, -v54, vcc
	v_mul_f32_e32 v0, v0, v1
	v_mul_f32_e32 v1, 0x3fb8aa3b, v0
	v_add_f32_e32 v0, v0, v0
	v_mul_f32_e32 v2, 0x3fb8aa3b, v0
	v_exp_f32_e32 v54, v1
	v_fmamk_f32 v1, v0, 0x3c088889, v189
	v_exp_f32_e32 v2, v2
	v_fmaak_f32 v1, v0, v1, 0x3e2aaaab
	v_fma_f32 v1, v0, v1, 0.5
	v_fma_f32 v1, v0, v1, 1.0
	v_mul_f32_e64 v1, v1, -v0
	v_sub_f32_e32 v2, 1.0, v2
	v_cmp_lt_f32_e32 vcc, s4, v0
	s_nop 1
	v_cndmask_b32_e32 v0, v2, v1, vcc
	v_sqrt_f32_e32 v110, v0
	v_add_f32_e32 v0, v23, v19
	v_add_f32_e32 v1, v7, v3
	s_waitcnt vmcnt(0)
	s_nop 7
	v_mov_b32_e32 v4, v170
	v_mov_b32_e32 v5, v171
	v_mov_b32_e32 v6, v172
	v_mov_b32_e32 v7, v173
	v_mov_b32_e32 v16, v144
	v_mov_b32_e32 v17, v145
	v_mov_b32_e32 v18, v166
	v_mov_b32_e32 v19, v167
	v_mov_b32_e32 v20, v180
	v_mov_b32_e32 v21, v181
	v_mov_b32_e32 v22, v202
	v_mov_b32_e32 v23, v203
	global_load_dwordx4 v[170:173], v168, s[10:11] offset:224
	global_load_dwordx2 v[144:145], v168, s[12:13] offset:224
	global_load_dwordx2 v[166:167], v168, s[12:13] offset:232
	global_load_dwordx2 v[180:181], v168, s[8:9] offset:224
	global_load_dwordx2 v[202:203], v168, s[8:9] offset:232
	v_mul_f32_e32 v1, 0xbfb8aa3b, v1
	v_exp_f32_e32 v1, v1
	v_mul_f32_e32 v0, 0xbfb8aa3b, v0
	v_exp_f32_e32 v0, v0
	v_add_f32_e32 v1, 1.0, v1
	v_rcp_f32_e32 v109, v1
	v_mul_f32_e32 v1, 0xbfb8aa3b, v55
	v_exp_f32_e32 v1, v1
	v_add_f32_e32 v0, 1.0, v0
	v_rcp_f32_e32 v0, v0
	v_add_f32_e32 v2, 1.0, v1
	v_cmp_gt_f32_e32 vcc, s28, v2
	v_mul_f32_e32 v0, 0xc1000000, v0
	v_add_f32_e32 v4, v24, v4
	v_cndmask_b32_e64 v3, 0, 32, vcc
	v_ldexp_f32 v2, v2, v3
	v_log_f32_e32 v2, v2
	v_add_f32_e32 v8, v8, v16
	v_mul_f32_e32 v8, 0xbfb8aa3b, v8
	v_exp_f32_e32 v8, v8
	v_mul_f32_e32 v3, 0x3f317217, v2
	v_fma_f32 v3, v2, s0, -v3
	v_fmac_f32_e32 v3, 0x3377d1cf, v2
	v_fmac_f32_e32 v3, 0x3f317217, v2
	v_cmp_lt_f32_e64 s[6:7], |v2|, s1
	v_add_f32_e32 v8, 1.0, v8
	v_rcp_f32_e32 v112, v8
	v_cndmask_b32_e64 v2, v2, v3, s[6:7]
	v_cndmask_b32_e32 v3, 0, v201, vcc
	v_sub_f32_e32 v2, v2, v3
	v_fmamk_f32 v3, v1, 0xbe800000, v188
	v_fma_f32 v3, -v1, v3, 0.5
	v_fma_f32 v3, -v1, v3, 1.0
	v_mul_f32_e32 v3, v1, v3
	v_cmp_gt_f32_e64 s[6:7], s3, v1
	v_cmp_gt_f32_e32 vcc, s2, v55
	v_mul_f32_e32 v8, 0xbfb8aa3b, v20
	v_cndmask_b32_e64 v1, v2, v3, s[6:7]
	v_cndmask_b32_e64 v1, v1, -v55, vcc
	v_mul_f32_e32 v0, v0, v1
	v_mul_f32_e32 v1, 0x3fb8aa3b, v0
	v_add_f32_e32 v0, v0, v0
	v_mul_f32_e32 v2, 0x3fb8aa3b, v0
	v_exp_f32_e32 v55, v1
	v_fmamk_f32 v1, v0, 0x3c088889, v189
	v_exp_f32_e32 v2, v2
	v_exp_f32_e32 v8, v8
	v_fmaak_f32 v1, v0, v1, 0x3e2aaaab
	v_fma_f32 v1, v0, v1, 0.5
	v_fma_f32 v1, v0, v1, 1.0
	v_mul_f32_e64 v1, v1, -v0
	v_sub_f32_e32 v2, 1.0, v2
	v_cmp_lt_f32_e32 vcc, s4, v0
	v_add_f32_e32 v16, 1.0, v8
	v_mul_f32_e32 v4, 0xbfb8aa3b, v4
	v_cndmask_b32_e32 v0, v2, v1, vcc
	v_cmp_gt_f32_e32 vcc, s28, v16
	v_exp_f32_e32 v4, v4
	v_sqrt_f32_e32 v111, v0
	v_cndmask_b32_e64 v24, 0, 32, vcc
	v_ldexp_f32 v16, v16, v24
	v_log_f32_e32 v16, v16
	v_add_f32_e32 v4, 1.0, v4
	v_rcp_f32_e32 v4, v4
	ds_read_b128 v[0:3], v124 offset:192
	v_mul_f32_e32 v24, 0x3f317217, v16
	v_fma_f32 v24, v16, s0, -v24
	v_fmac_f32_e32 v24, 0x3377d1cf, v16
	v_fmac_f32_e32 v24, 0x3f317217, v16
	v_cmp_lt_f32_e64 s[6:7], |v16|, s1
	v_mul_f32_e32 v4, 0xc1000000, v4
	s_nop 0
	v_cndmask_b32_e64 v16, v16, v24, s[6:7]
	v_cndmask_b32_e32 v24, 0, v201, vcc
	v_sub_f32_e32 v16, v16, v24
	v_fmamk_f32 v24, v8, 0xbe800000, v188
	v_fma_f32 v24, -v8, v24, 0.5
	v_fma_f32 v24, -v8, v24, 1.0
	v_mul_f32_e32 v24, v8, v24
	v_cmp_gt_f32_e64 s[6:7], s3, v8
	v_cmp_gt_f32_e32 vcc, s2, v20
	s_nop 0
	v_cndmask_b32_e64 v8, v16, v24, s[6:7]
	v_cndmask_b32_e64 v8, v8, -v20, vcc
	v_mul_f32_e32 v4, v4, v8
	v_mul_f32_e32 v8, 0x3fb8aa3b, v4
	v_add_f32_e32 v4, v4, v4
	v_mul_f32_e32 v16, 0x3fb8aa3b, v4
	v_exp_f32_e32 v116, v8
	v_fmamk_f32 v8, v4, 0x3c088889, v189
	v_exp_f32_e32 v16, v16
	v_fmaak_f32 v8, v4, v8, 0x3e2aaaab
	v_fma_f32 v8, v4, v8, 0.5
	v_fma_f32 v8, v4, v8, 1.0
	v_mul_f32_e64 v8, v8, -v4
	v_sub_f32_e32 v16, 1.0, v16
	v_cmp_lt_f32_e32 vcc, s4, v4
	s_nop 1
	v_cndmask_b32_e32 v4, v16, v8, vcc
	v_sqrt_f32_e32 v120, v4
	v_add_f32_e32 v4, v25, v5
	v_add_f32_e32 v5, v9, v17
	v_mul_f32_e32 v5, 0xbfb8aa3b, v5
	v_exp_f32_e32 v5, v5
	v_mul_f32_e32 v4, 0xbfb8aa3b, v4
	v_exp_f32_e32 v4, v4
	v_add_f32_e32 v5, 1.0, v5
	v_rcp_f32_e32 v113, v5
	v_mul_f32_e32 v5, 0xbfb8aa3b, v21
	v_exp_f32_e32 v5, v5
	v_add_f32_e32 v4, 1.0, v4
	v_rcp_f32_e32 v4, v4
	v_add_f32_e32 v8, 1.0, v5
	v_cmp_gt_f32_e32 vcc, s28, v8
	v_mul_f32_e32 v4, 0xc1000000, v4
	s_nop 0
	v_cndmask_b32_e64 v9, 0, 32, vcc
	v_ldexp_f32 v8, v8, v9
	v_log_f32_e32 v8, v8
	s_nop 0
	v_mul_f32_e32 v9, 0x3f317217, v8
	v_fma_f32 v9, v8, s0, -v9
	v_fmac_f32_e32 v9, 0x3377d1cf, v8
	v_fmac_f32_e32 v9, 0x3f317217, v8
	v_cmp_lt_f32_e64 s[6:7], |v8|, s1
	s_nop 1
	v_cndmask_b32_e64 v8, v8, v9, s[6:7]
	v_cndmask_b32_e32 v9, 0, v201, vcc
	v_sub_f32_e32 v8, v8, v9
	v_fmamk_f32 v9, v5, 0xbe800000, v188
	v_fma_f32 v9, -v5, v9, 0.5
	v_fma_f32 v9, -v5, v9, 1.0
	v_mul_f32_e32 v9, v5, v9
	v_cmp_gt_f32_e64 s[6:7], s3, v5
	v_cmp_gt_f32_e32 vcc, s2, v21
	s_nop 0
	v_cndmask_b32_e64 v5, v8, v9, s[6:7]
	v_cndmask_b32_e64 v5, v5, -v21, vcc
	v_mul_f32_e32 v4, v4, v5
	v_mul_f32_e32 v5, 0x3fb8aa3b, v4
	v_add_f32_e32 v4, v4, v4
	v_mul_f32_e32 v8, 0x3fb8aa3b, v4
	v_exp_f32_e32 v117, v5
	v_fmamk_f32 v5, v4, 0x3c088889, v189
	v_exp_f32_e32 v8, v8
	v_fmaak_f32 v5, v4, v5, 0x3e2aaaab
	v_fma_f32 v5, v4, v5, 0.5
	v_fma_f32 v5, v4, v5, 1.0
	v_mul_f32_e64 v5, v5, -v4
	v_sub_f32_e32 v8, 1.0, v8
	v_cmp_lt_f32_e32 vcc, s4, v4
	s_nop 1
	v_cndmask_b32_e32 v4, v8, v5, vcc
	v_add_f32_e32 v5, v10, v18
	v_mul_f32_e32 v5, 0xbfb8aa3b, v5
	v_exp_f32_e32 v5, v5
	v_sqrt_f32_e32 v121, v4
	v_add_f32_e32 v4, v26, v6
	v_mul_f32_e32 v4, 0xbfb8aa3b, v4
	v_add_f32_e32 v5, 1.0, v5
	v_rcp_f32_e32 v114, v5
	v_mul_f32_e32 v5, 0xbfb8aa3b, v22
	v_exp_f32_e32 v5, v5
	v_exp_f32_e32 v4, v4
	v_add_f32_e32 v6, 1.0, v5
	v_cmp_gt_f32_e32 vcc, s28, v6
	v_add_f32_e32 v4, 1.0, v4
	v_rcp_f32_e32 v4, v4
	v_cndmask_b32_e64 v8, 0, 32, vcc
	v_ldexp_f32 v6, v6, v8
	v_log_f32_e32 v6, v6
	v_mul_f32_e32 v4, 0xc1000000, v4
	v_mul_f32_e32 v8, 0x3f317217, v6
	v_fma_f32 v8, v6, s0, -v8
	v_fmac_f32_e32 v8, 0x3377d1cf, v6
	v_fmac_f32_e32 v8, 0x3f317217, v6
	v_cmp_lt_f32_e64 s[6:7], |v6|, s1
	s_nop 1
	v_cndmask_b32_e64 v6, v6, v8, s[6:7]
	v_cndmask_b32_e32 v8, 0, v201, vcc
	v_sub_f32_e32 v6, v6, v8
	v_fmamk_f32 v8, v5, 0xbe800000, v188
	v_fma_f32 v8, -v5, v8, 0.5
	v_fma_f32 v8, -v5, v8, 1.0
	v_mul_f32_e32 v8, v5, v8
	v_cmp_gt_f32_e64 s[6:7], s3, v5
	v_cmp_gt_f32_e32 vcc, s2, v22
	s_nop 0
	v_cndmask_b32_e64 v5, v6, v8, s[6:7]
	v_cndmask_b32_e64 v5, v5, -v22, vcc
	v_mul_f32_e32 v4, v4, v5
	v_mul_f32_e32 v5, 0x3fb8aa3b, v4
	v_add_f32_e32 v4, v4, v4
	v_mul_f32_e32 v6, 0x3fb8aa3b, v4
	v_exp_f32_e32 v118, v5
	v_fmamk_f32 v5, v4, 0x3c088889, v189
	v_exp_f32_e32 v6, v6
	v_fmaak_f32 v5, v4, v5, 0x3e2aaaab
	v_fma_f32 v5, v4, v5, 0.5
	v_fma_f32 v5, v4, v5, 1.0
	v_mul_f32_e64 v5, v5, -v4
	v_sub_f32_e32 v6, 1.0, v6
	v_cmp_lt_f32_e32 vcc, s4, v4
	s_nop 1
	v_cndmask_b32_e32 v4, v6, v5, vcc
	v_add_f32_e32 v5, v11, v19
	v_mul_f32_e32 v5, 0xbfb8aa3b, v5
	v_exp_f32_e32 v5, v5
	v_sqrt_f32_e32 v122, v4
	v_add_f32_e32 v4, v27, v7
	v_mul_f32_e32 v4, 0xbfb8aa3b, v4
	v_add_f32_e32 v5, 1.0, v5
	v_rcp_f32_e32 v115, v5
	v_mul_f32_e32 v5, 0xbfb8aa3b, v23
	v_exp_f32_e32 v5, v5
	v_exp_f32_e32 v4, v4
	v_add_f32_e32 v6, 1.0, v5
	v_cmp_gt_f32_e32 vcc, s28, v6
	v_add_f32_e32 v4, 1.0, v4
	v_rcp_f32_e32 v4, v4
	v_cndmask_b32_e64 v7, 0, 32, vcc
	v_ldexp_f32 v6, v6, v7
	v_log_f32_e32 v6, v6
	v_mul_f32_e32 v4, 0xc1000000, v4
	v_mul_f32_e32 v7, 0x3f317217, v6
	v_fma_f32 v7, v6, s0, -v7
	v_fmac_f32_e32 v7, 0x3377d1cf, v6
	v_fmac_f32_e32 v7, 0x3f317217, v6
	v_cmp_lt_f32_e64 s[6:7], |v6|, s1
	s_nop 1
	v_cndmask_b32_e64 v6, v6, v7, s[6:7]
	v_cndmask_b32_e32 v7, 0, v201, vcc
	v_sub_f32_e32 v6, v6, v7
	v_fmamk_f32 v7, v5, 0xbe800000, v188
	v_fma_f32 v7, -v5, v7, 0.5
	v_fma_f32 v7, -v5, v7, 1.0
	v_mul_f32_e32 v7, v5, v7
	v_cmp_gt_f32_e64 s[6:7], s3, v5
	v_cmp_gt_f32_e32 vcc, s2, v23
	s_nop 0
	v_cndmask_b32_e64 v5, v6, v7, s[6:7]
	v_cndmask_b32_e64 v5, v5, -v23, vcc
	s_waitcnt vmcnt(0)
	s_nop 7
	v_mov_b32_e32 v20, v170
	v_mov_b32_e32 v21, v171
	v_mov_b32_e32 v22, v172
	v_mov_b32_e32 v23, v173
	v_mov_b32_e32 v16, v144
	v_mov_b32_e32 v17, v145
	v_mov_b32_e32 v18, v166
	v_mov_b32_e32 v19, v167
	v_mov_b32_e32 v8, v180
	v_mov_b32_e32 v9, v181
	v_mov_b32_e32 v10, v202
	v_mov_b32_e32 v11, v203
	v_mul_f32_e32 v4, v4, v5
	v_mul_f32_e32 v5, 0x3fb8aa3b, v4
	v_add_f32_e32 v4, v4, v4
	v_mul_f32_e32 v6, 0x3fb8aa3b, v4
	v_exp_f32_e32 v119, v5
	v_fmamk_f32 v5, v4, 0x3c088889, v189
	v_exp_f32_e32 v6, v6
	v_fmaak_f32 v5, v4, v5, 0x3e2aaaab
	v_fma_f32 v5, v4, v5, 0.5
	v_fma_f32 v5, v4, v5, 1.0
	v_mul_f32_e64 v5, v5, -v4
	v_sub_f32_e32 v6, 1.0, v6
	v_cmp_lt_f32_e32 vcc, s4, v4
	s_waitcnt vmcnt(2)
	v_add_f32_e32 v20, v28, v20
	v_mul_f32_e32 v20, 0xbfb8aa3b, v20
	v_exp_f32_e32 v20, v20
	s_waitcnt vmcnt(1)
	v_add_f32_e32 v12, v12, v16
	v_mul_f32_e32 v12, 0xbfb8aa3b, v12
	v_exp_f32_e32 v12, v12
	v_add_f32_e32 v20, 1.0, v20
	s_waitcnt vmcnt(0)
	v_mul_f32_e32 v16, 0xbfb8aa3b, v8
	v_rcp_f32_e32 v20, v20
	v_exp_f32_e32 v16, v16
	v_cndmask_b32_e32 v4, v6, v5, vcc
	v_add_f32_e32 v12, 1.0, v12
	v_sqrt_f32_e32 v123, v4
	ds_read_b128 v[4:7], v124 offset:224
	v_rcp_f32_e32 v124, v12
	v_mul_f32_e32 v12, 0xc1000000, v20
	v_add_f32_e32 v20, 1.0, v16
	v_cmp_gt_f32_e32 vcc, s28, v20
	s_nop 1
	v_cndmask_b32_e64 v24, 0, 32, vcc
	v_ldexp_f32 v20, v20, v24
	v_log_f32_e32 v20, v20
	s_nop 0
	v_mul_f32_e32 v24, 0x3f317217, v20
	v_fma_f32 v24, v20, s0, -v24
	v_fmac_f32_e32 v24, 0x3377d1cf, v20
	v_fmac_f32_e32 v24, 0x3f317217, v20
	v_cmp_lt_f32_e64 s[6:7], |v20|, s1
	s_nop 1
	v_cndmask_b32_e64 v20, v20, v24, s[6:7]
	v_cndmask_b32_e32 v24, 0, v201, vcc
	v_sub_f32_e32 v20, v20, v24
	v_fmamk_f32 v24, v16, 0xbe800000, v188
	v_fma_f32 v24, -v16, v24, 0.5
	v_fma_f32 v24, -v16, v24, 1.0
	v_mul_f32_e32 v24, v16, v24
	v_cmp_gt_f32_e64 s[6:7], s3, v16
	v_cmp_gt_f32_e32 vcc, s2, v8
	s_nop 0
	v_cndmask_b32_e64 v16, v20, v24, s[6:7]
	v_cndmask_b32_e64 v8, v16, -v8, vcc
	v_mul_f32_e32 v8, v12, v8
	v_mul_f32_e32 v12, 0x3fb8aa3b, v8
	v_add_f32_e32 v8, v8, v8
	v_mul_f32_e32 v16, 0x3fb8aa3b, v8
	v_exp_f32_e32 v126, v12
	v_fmamk_f32 v12, v8, 0x3c088889, v189
	v_exp_f32_e32 v16, v16
	v_fmaak_f32 v12, v8, v12, 0x3e2aaaab
	v_fma_f32 v12, v8, v12, 0.5
	v_fma_f32 v12, v8, v12, 1.0
	v_mul_f32_e64 v12, v12, -v8
	v_sub_f32_e32 v16, 1.0, v16
	v_cmp_lt_f32_e32 vcc, s4, v8
	s_nop 1
	v_cndmask_b32_e32 v8, v16, v12, vcc
	v_add_f32_e32 v12, v13, v17
	v_mul_f32_e32 v12, 0xbfb8aa3b, v12
	v_exp_f32_e32 v12, v12
	v_sqrt_f32_e32 v128, v8
	v_add_f32_e32 v8, v29, v21
	v_mul_f32_e32 v8, 0xbfb8aa3b, v8
	v_add_f32_e32 v12, 1.0, v12
	v_rcp_f32_e32 v125, v12
	v_mul_f32_e32 v12, 0xbfb8aa3b, v9
	v_exp_f32_e32 v12, v12
	v_exp_f32_e32 v8, v8
	v_add_f32_e32 v13, 1.0, v12
	v_cmp_gt_f32_e32 vcc, s28, v13
	v_add_f32_e32 v8, 1.0, v8
	v_rcp_f32_e32 v8, v8
	v_cndmask_b32_e64 v16, 0, 32, vcc
	v_ldexp_f32 v13, v13, v16
	v_log_f32_e32 v13, v13
	v_mul_f32_e32 v8, 0xc1000000, v8
	v_mul_f32_e32 v16, 0x3f317217, v13
	v_fma_f32 v16, v13, s0, -v16
	v_fmac_f32_e32 v16, 0x3377d1cf, v13
	v_fmac_f32_e32 v16, 0x3f317217, v13
	v_cmp_lt_f32_e64 s[6:7], |v13|, s1
	s_nop 1
	v_cndmask_b32_e64 v13, v13, v16, s[6:7]
	v_cndmask_b32_e32 v16, 0, v201, vcc
	v_sub_f32_e32 v13, v13, v16
	v_fmamk_f32 v16, v12, 0xbe800000, v188
	v_fma_f32 v16, -v12, v16, 0.5
	v_fma_f32 v16, -v12, v16, 1.0
	v_mul_f32_e32 v16, v12, v16
	v_cmp_gt_f32_e64 s[6:7], s3, v12
	v_cmp_gt_f32_e32 vcc, s2, v9
	s_nop 0
	v_cndmask_b32_e64 v12, v13, v16, s[6:7]
	v_cndmask_b32_e64 v9, v12, -v9, vcc
	v_mul_f32_e32 v8, v8, v9
	v_mul_f32_e32 v9, 0x3fb8aa3b, v8
	v_add_f32_e32 v8, v8, v8
	v_mul_f32_e32 v12, 0x3fb8aa3b, v8
	v_exp_f32_e32 v127, v9
	v_fmamk_f32 v9, v8, 0x3c088889, v189
	v_exp_f32_e32 v12, v12
	v_fmaak_f32 v9, v8, v9, 0x3e2aaaab
	v_fma_f32 v9, v8, v9, 0.5
	v_fma_f32 v9, v8, v9, 1.0
	v_mul_f32_e64 v9, v9, -v8
	v_sub_f32_e32 v12, 1.0, v12
	v_cmp_lt_f32_e32 vcc, s4, v8
	s_nop 1
	v_cndmask_b32_e32 v8, v12, v9, vcc
	v_add_f32_e32 v9, v14, v18
	v_mul_f32_e32 v9, 0xbfb8aa3b, v9
	v_exp_f32_e32 v9, v9
	v_sqrt_f32_e32 v129, v8
	v_add_f32_e32 v8, v30, v22
	v_mul_f32_e32 v8, 0xbfb8aa3b, v8
	v_add_f32_e32 v9, 1.0, v9
	v_rcp_f32_e32 v130, v9
	v_mul_f32_e32 v9, 0xbfb8aa3b, v10
	v_exp_f32_e32 v9, v9
	v_exp_f32_e32 v8, v8
	v_add_f32_e32 v12, 1.0, v9
	v_cmp_gt_f32_e32 vcc, s28, v12
	v_add_f32_e32 v8, 1.0, v8
	v_rcp_f32_e32 v8, v8
	v_cndmask_b32_e64 v13, 0, 32, vcc
	v_ldexp_f32 v12, v12, v13
	v_log_f32_e32 v12, v12
	v_mul_f32_e32 v8, 0xc1000000, v8
	v_mul_f32_e32 v13, 0x3f317217, v12
	v_fma_f32 v13, v12, s0, -v13
	v_fmac_f32_e32 v13, 0x3377d1cf, v12
	v_fmac_f32_e32 v13, 0x3f317217, v12
	v_cmp_lt_f32_e64 s[6:7], |v12|, s1
	s_nop 1
	v_cndmask_b32_e64 v12, v12, v13, s[6:7]
	v_cndmask_b32_e32 v13, 0, v201, vcc
	v_sub_f32_e32 v12, v12, v13
	v_fmamk_f32 v13, v9, 0xbe800000, v188
	v_fma_f32 v13, -v9, v13, 0.5
	v_fma_f32 v13, -v9, v13, 1.0
	v_mul_f32_e32 v13, v9, v13
	v_cmp_gt_f32_e64 s[6:7], s3, v9
	v_cmp_gt_f32_e32 vcc, s2, v10
	s_nop 0
	v_cndmask_b32_e64 v9, v12, v13, s[6:7]
	v_cndmask_b32_e64 v9, v9, -v10, vcc
	v_mul_f32_e32 v8, v8, v9
	v_mul_f32_e32 v9, 0x3fb8aa3b, v8
	v_add_f32_e32 v8, v8, v8
	v_mul_f32_e32 v10, 0x3fb8aa3b, v8
	v_exp_f32_e32 v132, v9
	v_fmamk_f32 v9, v8, 0x3c088889, v189
	v_exp_f32_e32 v10, v10
	v_fmaak_f32 v9, v8, v9, 0x3e2aaaab
	v_fma_f32 v9, v8, v9, 0.5
	v_fma_f32 v9, v8, v9, 1.0
	v_mul_f32_e64 v9, v9, -v8
	v_sub_f32_e32 v10, 1.0, v10
	v_cmp_lt_f32_e32 vcc, s4, v8
	s_nop 1
	v_cndmask_b32_e32 v8, v10, v9, vcc
	v_add_f32_e32 v9, v15, v19
	v_mul_f32_e32 v9, 0xbfb8aa3b, v9
	v_exp_f32_e32 v9, v9
	v_sqrt_f32_e32 v134, v8
	v_add_f32_e32 v8, v31, v23
	v_mul_f32_e32 v8, 0xbfb8aa3b, v8
	v_add_f32_e32 v9, 1.0, v9
	v_rcp_f32_e32 v131, v9
	v_mul_f32_e32 v9, 0xbfb8aa3b, v11
	v_exp_f32_e32 v9, v9
	v_exp_f32_e32 v8, v8
	v_add_f32_e32 v10, 1.0, v9
	v_cmp_gt_f32_e32 vcc, s28, v10
	v_add_f32_e32 v8, 1.0, v8
	v_rcp_f32_e32 v8, v8
	v_cndmask_b32_e64 v12, 0, 32, vcc
	v_ldexp_f32 v10, v10, v12
	v_log_f32_e32 v10, v10
	v_mul_f32_e32 v8, 0xc1000000, v8
	v_mul_f32_e32 v12, 0x3f317217, v10
	v_fma_f32 v12, v10, s0, -v12
	v_fmac_f32_e32 v12, 0x3377d1cf, v10
	v_fmac_f32_e32 v12, 0x3f317217, v10
	v_cmp_lt_f32_e64 s[6:7], |v10|, s1
	s_nop 1
	v_cndmask_b32_e64 v10, v10, v12, s[6:7]
	v_cndmask_b32_e32 v12, 0, v201, vcc
	v_sub_f32_e32 v10, v10, v12
	v_fmamk_f32 v12, v9, 0xbe800000, v188
	v_fma_f32 v12, -v9, v12, 0.5
	v_fma_f32 v12, -v9, v12, 1.0
	v_mul_f32_e32 v12, v9, v12
	v_cmp_gt_f32_e64 s[6:7], s3, v9
	v_cmp_gt_f32_e32 vcc, s2, v11
	s_nop 0
	v_cndmask_b32_e64 v9, v10, v12, s[6:7]
	v_cndmask_b32_e64 v9, v9, -v11, vcc
	v_mul_f32_e32 v8, v8, v9
	v_mul_f32_e32 v9, 0x3fb8aa3b, v8
	v_add_f32_e32 v8, v8, v8
	v_mul_f32_e32 v10, 0x3fb8aa3b, v8
	v_exp_f32_e32 v133, v9
	v_fmamk_f32 v9, v8, 0x3c088889, v189
	v_exp_f32_e32 v10, v10
	v_fmaak_f32 v9, v8, v9, 0x3e2aaaab
	v_fma_f32 v9, v8, v9, 0.5
	v_fma_f32 v9, v8, v9, 1.0
	v_mul_f32_e64 v9, v9, -v8
	v_sub_f32_e32 v10, 1.0, v10
	v_cmp_lt_f32_e32 vcc, s4, v8
	s_nop 1
	v_cndmask_b32_e32 v8, v10, v9, vcc
	v_sqrt_f32_e32 v135, v8
	v_and_b32_e32 v8, 0x60, v191
	v_add_u32_e32 v9, -1, v191
	v_cmp_lt_i32_e32 vcc, v9, v8
	s_nop 1
	v_cndmask_b32_e32 v9, v9, v191, vcc
	v_and_b32_e32 v165, 15, v162
	v_mov_b32_dpp v10, v137 row_shr:1 row_mask:0xf bank_mask:0xf
	v_cmp_eq_u32_e32 vcc, 0, v165
	v_mov_b32_dpp v11, v139 row_shr:1 row_mask:0xf bank_mask:0xf
	v_mov_b32_dpp v9, v136 row_shr:1 row_mask:0xf bank_mask:0xf
	v_mov_b32_dpp v14, v68 row_shr:1 row_mask:0xf bank_mask:0xf
	s_waitcnt lgkmcnt(3)
	v_fma_f32 v10, v136, v10, v137
	v_cndmask_b32_e32 v12, v10, v137, vcc
	v_mov_b32_dpp v10, v138 row_shr:1 row_mask:0xf bank_mask:0xf
	s_waitcnt lgkmcnt(3)
	v_fma_f32 v11, v138, v11, v139
	v_cndmask_b32_e32 v16, v11, v139, vcc
	v_mov_b32_dpp v11, v141 row_shr:1 row_mask:0xf bank_mask:0xf
	v_mov_b32_dpp v15, v69 row_shr:1 row_mask:0xf bank_mask:0xf
	s_waitcnt lgkmcnt(2)
	v_mul_f32_e32 v10, v138, v10
	v_cndmask_b32_e32 v13, v10, v138, vcc
	v_mov_b32_dpp v10, v140 row_shr:1 row_mask:0xf bank_mask:0xf
	s_waitcnt lgkmcnt(2)
	v_fma_f32 v11, v140, v11, v141
	v_cndmask_b32_e32 v18, v11, v141, vcc
	v_mov_b32_dpp v11, v143 row_shr:1 row_mask:0xf bank_mask:0xf
	v_mul_f32_e32 v9, v136, v9
	s_waitcnt lgkmcnt(1)
	v_mul_f32_e32 v10, v140, v10
	v_cndmask_b32_e32 v17, v10, v140, vcc
	v_mov_b32_dpp v10, v142 row_shr:1 row_mask:0xf bank_mask:0xf
	s_waitcnt lgkmcnt(1)
	v_fma_f32 v11, v142, v11, v143
	v_cndmask_b32_e32 v20, v11, v143, vcc
	v_mov_b32_dpp v11, v63 row_shr:1 row_mask:0xf bank_mask:0xf
	v_cndmask_b32_e32 v9, v9, v136, vcc
	s_waitcnt lgkmcnt(1)
	v_mul_f32_e32 v10, v142, v10
	v_cndmask_b32_e32 v19, v10, v142, vcc
	v_mov_b32_dpp v10, v62 row_shr:1 row_mask:0xf bank_mask:0xf
	v_mov_b32_dpp v28, v76 row_shr:1 row_mask:0xf bank_mask:0xf
	v_mov_b32_dpp v29, v77 row_shr:1 row_mask:0xf bank_mask:0xf
	v_mov_b32_dpp v24, v78 row_shr:1 row_mask:0xf bank_mask:0xf
	v_mov_b32_dpp v25, v79 row_shr:1 row_mask:0xf bank_mask:0xf
	v_mov_b32_dpp v30, v86 row_shr:1 row_mask:0xf bank_mask:0xf
	v_mov_b32_dpp v31, v87 row_shr:1 row_mask:0xf bank_mask:0xf
	v_mov_b32_dpp v26, v92 row_shr:1 row_mask:0xf bank_mask:0xf
	v_mov_b32_dpp v27, v93 row_shr:1 row_mask:0xf bank_mask:0xf
	v_mov_b32_dpp v158, v96 row_shr:1 row_mask:0xf bank_mask:0xf
	v_mov_b32_dpp v159, v97 row_shr:1 row_mask:0xf bank_mask:0xf
	v_mov_b32_dpp v156, v98 row_shr:1 row_mask:0xf bank_mask:0xf
	v_mov_b32_dpp v157, v99 row_shr:1 row_mask:0xf bank_mask:0xf
	v_mov_b32_dpp v154, v52 row_shr:1 row_mask:0xf bank_mask:0xf
	v_mov_b32_dpp v155, v53 row_shr:1 row_mask:0xf bank_mask:0xf
	v_mov_b32_dpp v152, v54 row_shr:1 row_mask:0xf bank_mask:0xf
	v_mov_b32_dpp v153, v55 row_shr:1 row_mask:0xf bank_mask:0xf
	v_mov_b32_dpp v150, v116 row_shr:1 row_mask:0xf bank_mask:0xf
	v_mov_b32_dpp v151, v117 row_shr:1 row_mask:0xf bank_mask:0xf
	v_mov_b32_dpp v148, v118 row_shr:1 row_mask:0xf bank_mask:0xf
	v_mov_b32_dpp v149, v119 row_shr:1 row_mask:0xf bank_mask:0xf
	v_mov_b32_dpp v146, v126 row_shr:1 row_mask:0xf bank_mask:0xf
	v_mov_b32_dpp v147, v127 row_shr:1 row_mask:0xf bank_mask:0xf
	v_mov_b32_dpp v136, v132 row_shr:1 row_mask:0xf bank_mask:0xf
	v_mov_b32_dpp v137, v133 row_shr:1 row_mask:0xf bank_mask:0xf
	v_add_u32_e32 v21, -2, v191
	v_cmp_lt_i32_e64 s[6:7], v21, v8
	s_nop 1
	v_cndmask_b32_e64 v21, v21, v191, s[6:7]
	v_lshlrev_b32_e32 v166, 2, v21
	v_mov_b32_dpp v21, v9 row_shr:2 row_mask:0xf bank_mask:0xf
	v_mov_b32_dpp v22, v12 row_shr:2 row_mask:0xf bank_mask:0xf
	v_cmp_gt_u32_e64 s[6:7], 2, v165
	s_waitcnt lgkmcnt(1)
	v_mul_f32_e32 v21, v9, v21
	s_waitcnt lgkmcnt(0)
	v_fma_f32 v22, v9, v22, v12
	v_cndmask_b32_e64 v9, v21, v9, s[6:7]
	v_cndmask_b32_e64 v12, v22, v12, s[6:7]
	v_mov_b32_dpp v21, v13 row_shr:2 row_mask:0xf bank_mask:0xf
	v_mov_b32_dpp v22, v16 row_shr:2 row_mask:0xf bank_mask:0xf
	s_waitcnt lgkmcnt(1)
	v_mul_f32_e32 v21, v13, v21
	s_waitcnt lgkmcnt(0)
	v_fma_f32 v22, v13, v22, v16
	v_cndmask_b32_e64 v13, v21, v13, s[6:7]
	v_cndmask_b32_e64 v16, v22, v16, s[6:7]
	v_mov_b32_dpp v21, v17 row_shr:2 row_mask:0xf bank_mask:0xf
	v_mov_b32_dpp v22, v18 row_shr:2 row_mask:0xf bank_mask:0xf
	s_waitcnt lgkmcnt(1)
	v_mul_f32_e32 v21, v17, v21
	s_waitcnt lgkmcnt(0)
	v_fma_f32 v22, v17, v22, v18
	v_cndmask_b32_e64 v17, v21, v17, s[6:7]
	v_cndmask_b32_e64 v18, v22, v18, s[6:7]
	v_mov_b32_dpp v21, v19 row_shr:2 row_mask:0xf bank_mask:0xf
	v_mov_b32_dpp v22, v20 row_shr:2 row_mask:0xf bank_mask:0xf
	s_waitcnt lgkmcnt(1)
	v_mul_f32_e32 v21, v19, v21
	s_waitcnt lgkmcnt(0)
	v_fma_f32 v22, v19, v22, v20
	v_cndmask_b32_e64 v19, v21, v19, s[6:7]
	v_cndmask_b32_e64 v20, v22, v20, s[6:7]
	v_add_u32_e32 v21, -4, v191
	v_cmp_lt_i32_e64 s[8:9], v21, v8
	s_nop 1
	v_cndmask_b32_e64 v21, v21, v191, s[8:9]
	v_lshlrev_b32_e32 v167, 2, v21
	v_mov_b32_dpp v21, v9 row_shr:4 row_mask:0xf bank_mask:0xf
	v_mov_b32_dpp v22, v12 row_shr:4 row_mask:0xf bank_mask:0xf
	v_cmp_gt_u32_e64 s[8:9], 4, v165
	s_waitcnt lgkmcnt(1)
	v_mul_f32_e32 v21, v9, v21
	s_waitcnt lgkmcnt(0)
	v_fma_f32 v22, v9, v22, v12
	v_cndmask_b32_e64 v9, v21, v9, s[8:9]
	v_cndmask_b32_e64 v12, v22, v12, s[8:9]
	v_mov_b32_dpp v21, v13 row_shr:4 row_mask:0xf bank_mask:0xf
	v_mov_b32_dpp v22, v16 row_shr:4 row_mask:0xf bank_mask:0xf
	s_waitcnt lgkmcnt(1)
	v_mul_f32_e32 v21, v13, v21
	s_waitcnt lgkmcnt(0)
	v_fma_f32 v22, v13, v22, v16
	v_cndmask_b32_e64 v13, v21, v13, s[8:9]
	v_cndmask_b32_e64 v16, v22, v16, s[8:9]
	v_mov_b32_dpp v21, v17 row_shr:4 row_mask:0xf bank_mask:0xf
	v_mov_b32_dpp v22, v18 row_shr:4 row_mask:0xf bank_mask:0xf
	s_waitcnt lgkmcnt(1)
	v_mul_f32_e32 v21, v17, v21
	s_waitcnt lgkmcnt(0)
	v_fma_f32 v22, v17, v22, v18
	v_cndmask_b32_e64 v17, v21, v17, s[8:9]
	v_cndmask_b32_e64 v18, v22, v18, s[8:9]
	v_mov_b32_dpp v21, v19 row_shr:4 row_mask:0xf bank_mask:0xf
	v_mov_b32_dpp v22, v20 row_shr:4 row_mask:0xf bank_mask:0xf
	s_waitcnt lgkmcnt(1)
	v_mul_f32_e32 v21, v19, v21
	s_waitcnt lgkmcnt(0)
	v_fma_f32 v22, v19, v22, v20
	v_cndmask_b32_e64 v19, v21, v19, s[8:9]
	v_cndmask_b32_e64 v20, v22, v20, s[8:9]
	v_add_u32_e32 v21, -8, v191
	v_cmp_lt_i32_e64 s[10:11], v21, v8
	s_nop 1
	v_cndmask_b32_e64 v21, v21, v191, s[10:11]
	v_lshlrev_b32_e32 v168, 2, v21
	v_mov_b32_dpp v21, v9 row_shr:8 row_mask:0xf bank_mask:0xf
	v_mov_b32_dpp v22, v12 row_shr:8 row_mask:0xf bank_mask:0xf
	v_cmp_gt_u32_e64 s[10:11], 8, v165
	s_waitcnt lgkmcnt(1)
	v_mul_f32_e32 v21, v9, v21
	s_waitcnt lgkmcnt(0)
	v_fma_f32 v22, v9, v22, v12
	v_cndmask_b32_e64 v140, v21, v9, s[10:11]
	v_cndmask_b32_e64 v138, v22, v12, s[10:11]
	v_mov_b32_dpp v9, v13 row_shr:8 row_mask:0xf bank_mask:0xf
	v_mov_b32_dpp v12, v16 row_shr:8 row_mask:0xf bank_mask:0xf
	s_waitcnt lgkmcnt(1)
	v_mul_f32_e32 v9, v13, v9
	s_waitcnt lgkmcnt(0)
	v_fma_f32 v12, v13, v12, v16
	v_cndmask_b32_e64 v141, v9, v13, s[10:11]
	v_cndmask_b32_e64 v139, v12, v16, s[10:11]
	v_mov_b32_dpp v9, v17 row_shr:8 row_mask:0xf bank_mask:0xf
	v_mov_b32_dpp v12, v18 row_shr:8 row_mask:0xf bank_mask:0xf
	s_waitcnt lgkmcnt(1)
	v_mul_f32_e32 v9, v17, v9
	s_waitcnt lgkmcnt(0)
	v_fma_f32 v12, v17, v12, v18
	v_cndmask_b32_e64 v144, v9, v17, s[10:11]
	v_cndmask_b32_e64 v142, v12, v18, s[10:11]
	v_mov_b32_dpp v9, v19 row_shr:8 row_mask:0xf bank_mask:0xf
	v_mov_b32_dpp v12, v20 row_shr:8 row_mask:0xf bank_mask:0xf
	s_waitcnt lgkmcnt(1)
	v_mul_f32_e32 v9, v19, v9
	s_waitcnt lgkmcnt(0)
	v_fma_f32 v12, v19, v12, v20
	v_cndmask_b32_e64 v145, v9, v19, s[10:11]
	v_cndmask_b32_e64 v143, v12, v20, s[10:11]
	v_pk_mul_f32 v[12:13], v[32:33], v[60:61]
	v_add_u32_e32 v9, -16, v191
	v_pk_mul_f32 v[12:13], v[12:13], v[64:65]
	s_nop 1
	v_mov_b32_dpp v16, v12 row_shr:1 row_mask:0xf bank_mask:0xf
	v_mov_b32_dpp v17, v13 row_shr:1 row_mask:0xf bank_mask:0xf
	v_pk_mul_f32 v[10:11], v[62:63], v[10:11]
	v_cmp_lt_i32_e64 s[12:13], v9, v8
	v_cndmask_b32_e32 v11, v11, v63, vcc
	v_cndmask_b32_e32 v10, v10, v62, vcc
	s_waitcnt lgkmcnt(0)
	v_pk_fma_f32 v[16:17], v[62:63], v[16:17], v[12:13]
	v_cndmask_b32_e64 v8, v9, v191, s[12:13]
	v_cndmask_b32_e32 v17, v17, v13, vcc
	v_cndmask_b32_e32 v16, v16, v12, vcc
	v_mov_b32_dpp v20, v10 row_shr:2 row_mask:0xf bank_mask:0xf
	s_nop 1
	v_mov_b32_dpp v22, v16 row_shr:2 row_mask:0xf bank_mask:0xf
	v_mov_b32_dpp v21, v11 row_shr:2 row_mask:0xf bank_mask:0xf
	v_mov_b32_dpp v23, v17 row_shr:2 row_mask:0xf bank_mask:0xf
	v_lshlrev_b32_e32 v170, 2, v8
	v_mov_b32_dpp v18, v138 row_bcast:15 row_mask:0xa bank_mask:0xf
	v_mov_b32_dpp v19, v139 row_bcast:15 row_mask:0xa bank_mask:0xf
	s_waitcnt lgkmcnt(3)
	v_pk_mul_f32 v[20:21], v[10:11], v[20:21]
	s_waitcnt lgkmcnt(2)
	v_pk_fma_f32 v[22:23], v[10:11], v[22:23], v[16:17]
	v_cndmask_b32_e64 v21, v21, v11, s[6:7]
	v_cndmask_b32_e64 v20, v20, v10, s[6:7]
	v_cndmask_b32_e64 v17, v23, v17, s[6:7]
	v_cndmask_b32_e64 v16, v22, v16, s[6:7]
	s_waitcnt lgkmcnt(0)
	v_pk_fma_f32 v[12:13], v[140:141], v[18:19], v[138:139]
	v_mov_b32_dpp v18, v144 row_bcast:15 row_mask:0xa bank_mask:0xf
	v_mov_b32_dpp v19, v145 row_bcast:15 row_mask:0xa bank_mask:0xf
	v_mov_b32_dpp v22, v20 row_shr:4 row_mask:0xf bank_mask:0xf
	v_mov_b32_dpp v32, v16 row_shr:4 row_mask:0xf bank_mask:0xf
	v_mov_b32_dpp v23, v21 row_shr:4 row_mask:0xf bank_mask:0xf
	v_mov_b32_dpp v33, v17 row_shr:4 row_mask:0xf bank_mask:0xf
	s_waitcnt lgkmcnt(4)
	v_pk_mul_f32 v[10:11], v[144:145], v[18:19]
	v_pk_mul_f32 v[14:15], v[68:69], v[14:15]
	v_mov_b32_dpp v8, v140 row_bcast:15 row_mask:0xa bank_mask:0xf
	s_waitcnt lgkmcnt(2)
	v_pk_mul_f32 v[18:19], v[20:21], v[22:23]
	s_waitcnt lgkmcnt(1)
	v_pk_fma_f32 v[22:23], v[20:21], v[32:33], v[16:17]
	v_cndmask_b32_e64 v19, v19, v21, s[8:9]
	v_cndmask_b32_e64 v17, v23, v17, s[8:9]
	v_cndmask_b32_e64 v16, v22, v16, s[8:9]
	v_pk_mul_f32 v[22:23], v[34:35], v[66:67]
	v_cndmask_b32_e64 v18, v18, v20, s[8:9]
	v_pk_mul_f32 v[22:23], v[22:23], v[70:71]
	s_nop 1
	v_mov_b32_dpp v32, v22 row_shr:1 row_mask:0xf bank_mask:0xf
	v_mov_b32_dpp v33, v23 row_shr:1 row_mask:0xf bank_mask:0xf
	v_mov_b32_dpp v20, v18 row_shr:8 row_mask:0xf bank_mask:0xf
	v_mov_b32_dpp v21, v19 row_shr:8 row_mask:0xf bank_mask:0xf
	v_cndmask_b32_e32 v15, v15, v69, vcc
	v_cndmask_b32_e32 v14, v14, v68, vcc
	s_waitcnt lgkmcnt(2)
	v_pk_fma_f32 v[32:33], v[68:69], v[32:33], v[22:23]
	v_mov_b32_dpp v34, v16 row_shr:8 row_mask:0xf bank_mask:0xf
	v_cndmask_b32_e32 v23, v33, v23, vcc
	v_cndmask_b32_e32 v22, v32, v22, vcc
	v_mov_b32_dpp v35, v17 row_shr:8 row_mask:0xf bank_mask:0xf
	v_mov_b32_dpp v32, v14 row_shr:2 row_mask:0xf bank_mask:0xf
	v_mov_b32_dpp v62, v22 row_shr:2 row_mask:0xf bank_mask:0xf
	v_mov_b32_dpp v33, v15 row_shr:2 row_mask:0xf bank_mask:0xf
	v_mov_b32_dpp v63, v23 row_shr:2 row_mask:0xf bank_mask:0xf
	s_waitcnt lgkmcnt(6)
	v_pk_mul_f32 v[20:21], v[18:19], v[20:21]
	s_waitcnt lgkmcnt(4)
	v_pk_fma_f32 v[34:35], v[18:19], v[34:35], v[16:17]
	v_cndmask_b32_e64 v65, v21, v19, s[10:11]
	v_cndmask_b32_e64 v64, v20, v18, s[10:11]
	s_waitcnt lgkmcnt(1)
	v_pk_mul_f32 v[18:19], v[14:15], v[32:33]
	s_waitcnt lgkmcnt(0)
	v_pk_fma_f32 v[20:21], v[14:15], v[62:63], v[22:23]
	v_cndmask_b32_e64 v15, v19, v15, s[6:7]
	v_cndmask_b32_e64 v14, v18, v14, s[6:7]
	v_cndmask_b32_e64 v19, v21, v23, s[6:7]
	v_cndmask_b32_e64 v18, v20, v22, s[6:7]
	v_mov_b32_dpp v20, v14 row_shr:4 row_mask:0xf bank_mask:0xf
	s_nop 1
	v_mov_b32_dpp v22, v18 row_shr:4 row_mask:0xf bank_mask:0xf
	v_mov_b32_dpp v21, v15 row_shr:4 row_mask:0xf bank_mask:0xf
	v_mov_b32_dpp v23, v19 row_shr:4 row_mask:0xf bank_mask:0xf
	v_cndmask_b32_e64 v67, v35, v17, s[10:11]
	v_cndmask_b32_e64 v66, v34, v16, s[10:11]
	v_mov_b32_dpp v9, v141 row_bcast:15 row_mask:0xa bank_mask:0xf
	s_waitcnt lgkmcnt(2)
	v_pk_mul_f32 v[20:21], v[14:15], v[20:21]
	s_waitcnt lgkmcnt(1)
	v_pk_fma_f32 v[22:23], v[14:15], v[22:23], v[18:19]
	v_cndmask_b32_e64 v15, v21, v15, s[8:9]
	v_cndmask_b32_e64 v14, v20, v14, s[8:9]
	v_cndmask_b32_e64 v19, v23, v19, s[8:9]
	v_cndmask_b32_e64 v18, v22, v18, s[8:9]
	v_mov_b32_dpp v20, v14 row_shr:8 row_mask:0xf bank_mask:0xf
	s_nop 1
	v_mov_b32_dpp v22, v18 row_shr:8 row_mask:0xf bank_mask:0xf
	v_mov_b32_dpp v21, v15 row_shr:8 row_mask:0xf bank_mask:0xf
	v_mov_b32_dpp v23, v19 row_shr:8 row_mask:0xf bank_mask:0xf
	v_mov_b32_dpp v60, v142 row_bcast:15 row_mask:0xa bank_mask:0xf
	v_mov_b32_dpp v61, v143 row_bcast:15 row_mask:0xa bank_mask:0xf
	v_mov_b32_dpp v16, v64 row_bcast:15 row_mask:0xa bank_mask:0xf
	s_waitcnt lgkmcnt(4)
	v_pk_mul_f32 v[20:21], v[14:15], v[20:21]
	s_waitcnt lgkmcnt(3)
	v_pk_fma_f32 v[22:23], v[14:15], v[22:23], v[18:19]
	v_cndmask_b32_e64 v69, v21, v15, s[10:11]
	v_cndmask_b32_e64 v68, v20, v14, s[10:11]
	v_cndmask_b32_e64 v71, v23, v19, s[10:11]
	v_cndmask_b32_e64 v70, v22, v18, s[10:11]
	v_mov_b32_dpp v32, v66 row_bcast:15 row_mask:0xa bank_mask:0xf
	v_mov_b32_dpp v17, v65 row_bcast:15 row_mask:0xa bank_mask:0xf
	v_mov_b32_dpp v33, v67 row_bcast:15 row_mask:0xa bank_mask:0xf
	v_mov_b32_dpp v18, v68 row_bcast:15 row_mask:0xa bank_mask:0xf
	v_mov_b32_dpp v34, v70 row_bcast:15 row_mask:0xa bank_mask:0xf
	v_mov_b32_dpp v19, v69 row_bcast:15 row_mask:0xa bank_mask:0xf
	v_mov_b32_dpp v35, v71 row_bcast:15 row_mask:0xa bank_mask:0xf
	v_pk_mul_f32 v[8:9], v[140:141], v[8:9]
	s_waitcnt lgkmcnt(8)
	v_pk_fma_f32 v[14:15], v[144:145], v[60:61], v[142:143]
	s_waitcnt lgkmcnt(5)
	v_pk_mul_f32 v[20:21], v[64:65], v[16:17]
	s_waitcnt lgkmcnt(4)
	v_pk_fma_f32 v[16:17], v[64:65], v[32:33], v[66:67]
	s_waitcnt lgkmcnt(1)
	v_pk_mul_f32 v[22:23], v[68:69], v[18:19]
	s_waitcnt lgkmcnt(0)
	v_pk_fma_f32 v[18:19], v[68:69], v[34:35], v[70:71]
	v_pk_mul_f32 v[32:33], v[36:37], v[72:73]
	v_pk_mul_f32 v[28:29], v[76:77], v[28:29]
	v_pk_mul_f32 v[32:33], v[32:33], v[80:81]
	s_nop 1
	v_mov_b32_dpp v34, v32 row_shr:1 row_mask:0xf bank_mask:0xf
	v_mov_b32_dpp v35, v33 row_shr:1 row_mask:0xf bank_mask:0xf
	v_cndmask_b32_e32 v29, v29, v77, vcc
	v_cndmask_b32_e32 v28, v28, v76, vcc
	v_pk_mul_f32 v[38:39], v[38:39], v[74:75]
	v_pk_mul_f32 v[24:25], v[78:79], v[24:25]
	s_waitcnt lgkmcnt(0)
	v_pk_fma_f32 v[34:35], v[76:77], v[34:35], v[32:33]
	v_pk_mul_f32 v[38:39], v[38:39], v[82:83]
	v_cndmask_b32_e32 v33, v35, v33, vcc
	v_cndmask_b32_e32 v32, v34, v32, vcc
	v_mov_b32_dpp v34, v28 row_shr:2 row_mask:0xf bank_mask:0xf
	v_mov_b32_dpp v35, v29 row_shr:2 row_mask:0xf bank_mask:0xf
	v_mov_b32_dpp v36, v32 row_shr:2 row_mask:0xf bank_mask:0xf
	v_mov_b32_dpp v37, v33 row_shr:2 row_mask:0xf bank_mask:0xf
	v_mov_b32_dpp v60, v38 row_shr:1 row_mask:0xf bank_mask:0xf
	v_mov_b32_dpp v61, v39 row_shr:1 row_mask:0xf bank_mask:0xf
	s_waitcnt lgkmcnt(4)
	v_pk_mul_f32 v[34:35], v[28:29], v[34:35]
	v_cndmask_b32_e32 v25, v25, v79, vcc
	s_waitcnt lgkmcnt(2)
	v_pk_fma_f32 v[36:37], v[28:29], v[36:37], v[32:33]
	v_cndmask_b32_e64 v29, v35, v29, s[6:7]
	v_cndmask_b32_e64 v28, v34, v28, s[6:7]
	v_cndmask_b32_e64 v33, v37, v33, s[6:7]
	v_cndmask_b32_e64 v32, v36, v32, s[6:7]
	v_mov_b32_dpp v34, v28 row_shr:4 row_mask:0xf bank_mask:0xf
	v_mov_b32_dpp v35, v29 row_shr:4 row_mask:0xf bank_mask:0xf
	v_mov_b32_dpp v36, v32 row_shr:4 row_mask:0xf bank_mask:0xf
	v_mov_b32_dpp v37, v33 row_shr:4 row_mask:0xf bank_mask:0xf
	v_cndmask_b32_e32 v24, v24, v78, vcc
	v_pk_mul_f32 v[40:41], v[40:41], v[84:85]
	s_waitcnt lgkmcnt(2)
	v_pk_mul_f32 v[34:35], v[28:29], v[34:35]
	v_pk_mul_f32 v[40:41], v[40:41], v[88:89]
	s_waitcnt lgkmcnt(0)
	v_pk_fma_f32 v[36:37], v[28:29], v[36:37], v[32:33]
	v_cndmask_b32_e64 v29, v35, v29, s[8:9]
	v_cndmask_b32_e64 v28, v34, v28, s[8:9]
	s_nop 1
	v_mov_b32_dpp v34, v28 row_shr:8 row_mask:0xf bank_mask:0xf
	v_mov_b32_dpp v35, v29 row_shr:8 row_mask:0xf bank_mask:0xf
	v_cndmask_b32_e64 v33, v37, v33, s[8:9]
	v_cndmask_b32_e64 v32, v36, v32, s[8:9]
	s_nop 1
	v_mov_b32_dpp v36, v32 row_shr:8 row_mask:0xf bank_mask:0xf
	v_mov_b32_dpp v37, v33 row_shr:8 row_mask:0xf bank_mask:0xf
	s_waitcnt lgkmcnt(2)
	v_pk_mul_f32 v[34:35], v[28:29], v[34:35]
	v_pk_mul_f32 v[30:31], v[86:87], v[30:31]
	v_cndmask_b32_e64 v73, v35, v29, s[10:11]
	v_cndmask_b32_e64 v72, v34, v28, s[10:11]
	s_waitcnt lgkmcnt(0)
	v_pk_fma_f32 v[36:37], v[28:29], v[36:37], v[32:33]
	v_pk_fma_f32 v[28:29], v[78:79], v[60:61], v[38:39]
	v_mov_b32_dpp v34, v24 row_shr:2 row_mask:0xf bank_mask:0xf
	v_cndmask_b32_e32 v29, v29, v39, vcc
	v_cndmask_b32_e32 v28, v28, v38, vcc
	v_mov_b32_dpp v35, v25 row_shr:2 row_mask:0xf bank_mask:0xf
	s_nop 1
	v_mov_b32_dpp v38, v28 row_shr:2 row_mask:0xf bank_mask:0xf
	v_mov_b32_dpp v39, v29 row_shr:2 row_mask:0xf bank_mask:0xf
	v_cndmask_b32_e64 v75, v37, v33, s[10:11]
	v_cndmask_b32_e64 v74, v36, v32, s[10:11]
	s_waitcnt lgkmcnt(2)
	v_pk_mul_f32 v[34:35], v[24:25], v[34:35]
	v_mov_b32_dpp v32, v72 row_bcast:15 row_mask:0xa bank_mask:0xf
	s_waitcnt lgkmcnt(1)
	v_pk_fma_f32 v[36:37], v[24:25], v[38:39], v[28:29]
	v_cndmask_b32_e64 v25, v35, v25, s[6:7]
	v_cndmask_b32_e64 v24, v34, v24, s[6:7]
	s_nop 1
	v_mov_b32_dpp v34, v24 row_shr:4 row_mask:0xf bank_mask:0xf
	v_mov_b32_dpp v35, v25 row_shr:4 row_mask:0xf bank_mask:0xf
	v_cndmask_b32_e64 v29, v37, v29, s[6:7]
	v_cndmask_b32_e64 v28, v36, v28, s[6:7]
	s_nop 1
	v_mov_b32_dpp v36, v28 row_shr:4 row_mask:0xf bank_mask:0xf
	v_mov_b32_dpp v37, v29 row_shr:4 row_mask:0xf bank_mask:0xf
	s_waitcnt lgkmcnt(2)
	v_pk_mul_f32 v[34:35], v[24:25], v[34:35]
	v_mov_b32_dpp v33, v73 row_bcast:15 row_mask:0xa bank_mask:0xf
	v_cndmask_b32_e64 v35, v35, v25, s[8:9]
	v_cndmask_b32_e64 v34, v34, v24, s[8:9]
	s_nop 1
	v_mov_b32_dpp v60, v34 row_shr:8 row_mask:0xf bank_mask:0xf
	v_mov_b32_dpp v61, v35 row_shr:8 row_mask:0xf bank_mask:0xf
	s_waitcnt lgkmcnt(3)
	v_pk_fma_f32 v[36:37], v[24:25], v[36:37], v[28:29]
	v_mov_b32_dpp v38, v74 row_bcast:15 row_mask:0xa bank_mask:0xf
	v_cndmask_b32_e64 v37, v37, v29, s[8:9]
	v_cndmask_b32_e64 v36, v36, v28, s[8:9]
	s_waitcnt lgkmcnt(3)
	v_pk_mul_f32 v[28:29], v[72:73], v[32:33]
	s_waitcnt lgkmcnt(1)
	v_pk_mul_f32 v[32:33], v[34:35], v[60:61]
	v_mov_b32_dpp v60, v40 row_shr:1 row_mask:0xf bank_mask:0xf
	v_mov_b32_dpp v61, v41 row_shr:1 row_mask:0xf bank_mask:0xf
	v_mov_b32_dpp v39, v75 row_bcast:15 row_mask:0xa bank_mask:0xf
	v_mov_b32_dpp v62, v36 row_shr:8 row_mask:0xf bank_mask:0xf
	v_mov_b32_dpp v63, v37 row_shr:8 row_mask:0xf bank_mask:0xf
	v_cndmask_b32_e64 v79, v33, v35, s[10:11]
	v_cndmask_b32_e64 v78, v32, v34, s[10:11]
	s_waitcnt lgkmcnt(3)
	v_pk_fma_f32 v[32:33], v[86:87], v[60:61], v[40:41]
	v_cndmask_b32_e32 v31, v31, v87, vcc
	v_cndmask_b32_e32 v30, v30, v86, vcc
	v_cndmask_b32_e32 v33, v33, v41, vcc
	v_cndmask_b32_e32 v32, v32, v40, vcc
	s_waitcnt lgkmcnt(2)
	v_pk_fma_f32 v[24:25], v[72:73], v[38:39], v[74:75]
	s_waitcnt lgkmcnt(0)
	v_pk_fma_f32 v[38:39], v[34:35], v[62:63], v[36:37]
	v_mov_b32_dpp v34, v30 row_shr:2 row_mask:0xf bank_mask:0xf
	v_mov_b32_dpp v40, v32 row_shr:2 row_mask:0xf bank_mask:0xf
	v_mov_b32_dpp v35, v31 row_shr:2 row_mask:0xf bank_mask:0xf
	v_mov_b32_dpp v41, v33 row_shr:2 row_mask:0xf bank_mask:0xf
	v_cndmask_b32_e64 v77, v39, v37, s[10:11]
	v_cndmask_b32_e64 v76, v38, v36, s[10:11]
	v_mov_b32_dpp v36, v78 row_bcast:15 row_mask:0xa bank_mask:0xf
	s_waitcnt lgkmcnt(2)
	v_pk_mul_f32 v[34:35], v[30:31], v[34:35]
	s_waitcnt lgkmcnt(1)
	v_pk_fma_f32 v[38:39], v[30:31], v[40:41], v[32:33]
	v_cndmask_b32_e64 v35, v35, v31, s[6:7]
	v_cndmask_b32_e64 v34, v34, v30, s[6:7]
	v_cndmask_b32_e64 v33, v39, v33, s[6:7]
	v_cndmask_b32_e64 v32, v38, v32, s[6:7]
	v_mov_b32_dpp v37, v79 row_bcast:15 row_mask:0xa bank_mask:0xf
	v_mov_b32_dpp v38, v34 row_shr:4 row_mask:0xf bank_mask:0xf
	v_mov_b32_dpp v40, v32 row_shr:4 row_mask:0xf bank_mask:0xf
	v_mov_b32_dpp v39, v35 row_shr:4 row_mask:0xf bank_mask:0xf
	v_mov_b32_dpp v41, v33 row_shr:4 row_mask:0xf bank_mask:0xf
	s_waitcnt lgkmcnt(4)
	v_pk_mul_f32 v[30:31], v[78:79], v[36:37]
	v_pk_mul_f32 v[26:27], v[92:93], v[26:27]
	v_mov_b32_dpp v60, v76 row_bcast:15 row_mask:0xa bank_mask:0xf
	s_waitcnt lgkmcnt(2)
	v_pk_mul_f32 v[36:37], v[34:35], v[38:39]
	s_waitcnt lgkmcnt(1)
	v_pk_fma_f32 v[38:39], v[34:35], v[40:41], v[32:33]
	v_cndmask_b32_e64 v35, v37, v35, s[8:9]
	v_cndmask_b32_e64 v33, v39, v33, s[8:9]
	v_cndmask_b32_e64 v32, v38, v32, s[8:9]
	v_pk_mul_f32 v[38:39], v[42:43], v[90:91]
	v_cndmask_b32_e64 v34, v36, v34, s[8:9]
	v_pk_mul_f32 v[38:39], v[38:39], v[94:95]
	s_nop 1
	v_mov_b32_dpp v40, v38 row_shr:1 row_mask:0xf bank_mask:0xf
	v_mov_b32_dpp v41, v39 row_shr:1 row_mask:0xf bank_mask:0xf
	v_mov_b32_dpp v36, v34 row_shr:8 row_mask:0xf bank_mask:0xf
	v_mov_b32_dpp v37, v35 row_shr:8 row_mask:0xf bank_mask:0xf
	v_cndmask_b32_e32 v27, v27, v93, vcc
	v_cndmask_b32_e32 v26, v26, v92, vcc
	s_waitcnt lgkmcnt(2)
	v_pk_fma_f32 v[40:41], v[92:93], v[40:41], v[38:39]
	v_mov_b32_dpp v42, v32 row_shr:8 row_mask:0xf bank_mask:0xf
	v_cndmask_b32_e32 v39, v41, v39, vcc
	v_cndmask_b32_e32 v38, v40, v38, vcc
	v_mov_b32_dpp v43, v33 row_shr:8 row_mask:0xf bank_mask:0xf
	v_mov_b32_dpp v40, v26 row_shr:2 row_mask:0xf bank_mask:0xf
	v_mov_b32_dpp v62, v38 row_shr:2 row_mask:0xf bank_mask:0xf
	v_mov_b32_dpp v41, v27 row_shr:2 row_mask:0xf bank_mask:0xf
	v_mov_b32_dpp v63, v39 row_shr:2 row_mask:0xf bank_mask:0xf
	s_waitcnt lgkmcnt(6)
	v_pk_mul_f32 v[36:37], v[34:35], v[36:37]
	s_waitcnt lgkmcnt(4)
	v_pk_fma_f32 v[42:43], v[34:35], v[42:43], v[32:33]
	v_cndmask_b32_e64 v81, v37, v35, s[10:11]
	v_cndmask_b32_e64 v80, v36, v34, s[10:11]
	s_waitcnt lgkmcnt(1)
	v_pk_mul_f32 v[34:35], v[26:27], v[40:41]
	s_waitcnt lgkmcnt(0)
	v_pk_fma_f32 v[36:37], v[26:27], v[62:63], v[38:39]
	v_cndmask_b32_e64 v27, v35, v27, s[6:7]
	v_cndmask_b32_e64 v26, v34, v26, s[6:7]
	v_cndmask_b32_e64 v35, v37, v39, s[6:7]
	v_cndmask_b32_e64 v34, v36, v38, s[6:7]
	v_mov_b32_dpp v36, v26 row_shr:4 row_mask:0xf bank_mask:0xf
	s_nop 1
	v_mov_b32_dpp v38, v34 row_shr:4 row_mask:0xf bank_mask:0xf
	v_mov_b32_dpp v37, v27 row_shr:4 row_mask:0xf bank_mask:0xf
	v_mov_b32_dpp v39, v35 row_shr:4 row_mask:0xf bank_mask:0xf
	v_cndmask_b32_e64 v83, v43, v33, s[10:11]
	v_cndmask_b32_e64 v82, v42, v32, s[10:11]
	v_mov_b32_dpp v61, v77 row_bcast:15 row_mask:0xa bank_mask:0xf
	s_waitcnt lgkmcnt(2)
	v_pk_mul_f32 v[36:37], v[26:27], v[36:37]
	s_waitcnt lgkmcnt(1)
	v_pk_fma_f32 v[38:39], v[26:27], v[38:39], v[34:35]
	v_cndmask_b32_e64 v27, v37, v27, s[8:9]
	v_cndmask_b32_e64 v26, v36, v26, s[8:9]
	v_cndmask_b32_e64 v35, v39, v35, s[8:9]
	v_cndmask_b32_e64 v34, v38, v34, s[8:9]
	v_mov_b32_dpp v36, v26 row_shr:8 row_mask:0xf bank_mask:0xf
	s_nop 1
	v_mov_b32_dpp v38, v34 row_shr:8 row_mask:0xf bank_mask:0xf
	v_mov_b32_dpp v37, v27 row_shr:8 row_mask:0xf bank_mask:0xf
	v_mov_b32_dpp v39, v35 row_shr:8 row_mask:0xf bank_mask:0xf
	v_mov_b32_dpp v32, v80 row_bcast:15 row_mask:0xa bank_mask:0xf
	v_mov_b32_dpp v40, v82 row_bcast:15 row_mask:0xa bank_mask:0xf
	v_mov_b32_dpp v33, v81 row_bcast:15 row_mask:0xa bank_mask:0xf
	s_waitcnt lgkmcnt(4)
	v_pk_mul_f32 v[36:37], v[26:27], v[36:37]
	s_waitcnt lgkmcnt(3)
	v_pk_fma_f32 v[38:39], v[26:27], v[38:39], v[34:35]
	v_cndmask_b32_e64 v85, v37, v27, s[10:11]
	v_cndmask_b32_e64 v84, v36, v26, s[10:11]
	v_cndmask_b32_e64 v87, v39, v35, s[10:11]
	v_cndmask_b32_e64 v86, v38, v34, s[10:11]
	v_mov_b32_dpp v41, v83 row_bcast:15 row_mask:0xa bank_mask:0xf
	v_mov_b32_dpp v34, v84 row_bcast:15 row_mask:0xa bank_mask:0xf
	v_mov_b32_dpp v42, v86 row_bcast:15 row_mask:0xa bank_mask:0xf
	v_mov_b32_dpp v35, v85 row_bcast:15 row_mask:0xa bank_mask:0xf
	v_mov_b32_dpp v43, v87 row_bcast:15 row_mask:0xa bank_mask:0xf
	v_pk_fma_f32 v[26:27], v[78:79], v[60:61], v[76:77]
	s_waitcnt lgkmcnt(5)
	v_pk_mul_f32 v[36:37], v[80:81], v[32:33]
	s_waitcnt lgkmcnt(4)
	v_pk_fma_f32 v[32:33], v[80:81], v[40:41], v[82:83]
	s_waitcnt lgkmcnt(1)
	v_pk_mul_f32 v[38:39], v[84:85], v[34:35]
	s_waitcnt lgkmcnt(0)
	v_pk_fma_f32 v[34:35], v[84:85], v[42:43], v[86:87]
	v_pk_mul_f32 v[40:41], v[48:49], v[56:57]
	v_pk_mul_f32 v[48:49], v[96:97], v[158:159]
	v_pk_mul_f32 v[40:41], v[40:41], v[100:101]
	s_nop 1
	v_mov_b32_dpp v42, v40 row_shr:1 row_mask:0xf bank_mask:0xf
	v_mov_b32_dpp v43, v41 row_shr:1 row_mask:0xf bank_mask:0xf
	v_cndmask_b32_e32 v49, v49, v97, vcc
	v_cndmask_b32_e32 v48, v48, v96, vcc
	v_pk_mul_f32 v[50:51], v[50:51], v[58:59]
	v_pk_mul_f32 v[44:45], v[44:45], v[104:105]
	s_waitcnt lgkmcnt(0)
	v_pk_fma_f32 v[42:43], v[96:97], v[42:43], v[40:41]
	v_pk_mul_f32 v[50:51], v[50:51], v[102:103]
	v_cndmask_b32_e32 v41, v43, v41, vcc
	v_cndmask_b32_e32 v40, v42, v40, vcc
	v_mov_b32_dpp v42, v48 row_shr:2 row_mask:0xf bank_mask:0xf
	v_mov_b32_dpp v43, v49 row_shr:2 row_mask:0xf bank_mask:0xf
	v_mov_b32_dpp v56, v40 row_shr:2 row_mask:0xf bank_mask:0xf
	v_mov_b32_dpp v57, v41 row_shr:2 row_mask:0xf bank_mask:0xf
	v_mov_b32_dpp v58, v50 row_shr:1 row_mask:0xf bank_mask:0xf
	v_mov_b32_dpp v59, v51 row_shr:1 row_mask:0xf bank_mask:0xf
	s_waitcnt lgkmcnt(4)
	v_pk_mul_f32 v[42:43], v[48:49], v[42:43]
	v_pk_mul_f32 v[44:45], v[44:45], v[106:107]
	s_waitcnt lgkmcnt(2)
	v_pk_fma_f32 v[56:57], v[48:49], v[56:57], v[40:41]
	v_cndmask_b32_e64 v43, v43, v49, s[6:7]
	v_cndmask_b32_e64 v42, v42, v48, s[6:7]
	v_cndmask_b32_e64 v41, v57, v41, s[6:7]
	v_cndmask_b32_e64 v40, v56, v40, s[6:7]
	v_mov_b32_dpp v48, v42 row_shr:4 row_mask:0xf bank_mask:0xf
	v_mov_b32_dpp v49, v43 row_shr:4 row_mask:0xf bank_mask:0xf
	v_mov_b32_dpp v56, v40 row_shr:4 row_mask:0xf bank_mask:0xf
	v_mov_b32_dpp v57, v41 row_shr:4 row_mask:0xf bank_mask:0xf
	v_pk_mul_f32 v[46:47], v[46:47], v[108:109]
	v_pk_mul_f32 v[62:63], v[54:55], v[152:153]
	s_waitcnt lgkmcnt(2)
	v_pk_mul_f32 v[48:49], v[42:43], v[48:49]
	v_pk_mul_f32 v[46:47], v[46:47], v[110:111]
	s_waitcnt lgkmcnt(0)
	v_pk_fma_f32 v[56:57], v[42:43], v[56:57], v[40:41]
	v_cndmask_b32_e64 v43, v49, v43, s[8:9]
	v_cndmask_b32_e64 v42, v48, v42, s[8:9]
	s_nop 1
	v_mov_b32_dpp v48, v42 row_shr:8 row_mask:0xf bank_mask:0xf
	v_mov_b32_dpp v49, v43 row_shr:8 row_mask:0xf bank_mask:0xf
	v_cndmask_b32_e64 v41, v57, v41, s[8:9]
	v_cndmask_b32_e64 v40, v56, v40, s[8:9]
	s_nop 1
	v_mov_b32_dpp v56, v40 row_shr:8 row_mask:0xf bank_mask:0xf
	v_mov_b32_dpp v57, v41 row_shr:8 row_mask:0xf bank_mask:0xf
	s_waitcnt lgkmcnt(2)
	v_pk_mul_f32 v[48:49], v[42:43], v[48:49]
	s_waitcnt lgkmcnt(0)
	v_pk_fma_f32 v[56:57], v[42:43], v[56:57], v[40:41]
	v_cndmask_b32_e64 v89, v49, v43, s[10:11]
	v_cndmask_b32_e64 v88, v48, v42, s[10:11]
	v_pk_mul_f32 v[42:43], v[98:99], v[156:157]
	v_pk_fma_f32 v[48:49], v[98:99], v[58:59], v[50:51]
	v_cndmask_b32_e32 v43, v43, v99, vcc
	v_cndmask_b32_e32 v42, v42, v98, vcc
	v_cndmask_b32_e32 v49, v49, v51, vcc
	v_cndmask_b32_e32 v48, v48, v50, vcc
	v_mov_b32_dpp v50, v42 row_shr:2 row_mask:0xf bank_mask:0xf
	s_nop 1
	v_mov_b32_dpp v58, v48 row_shr:2 row_mask:0xf bank_mask:0xf
	v_mov_b32_dpp v51, v43 row_shr:2 row_mask:0xf bank_mask:0xf
	v_mov_b32_dpp v59, v49 row_shr:2 row_mask:0xf bank_mask:0xf
	v_cndmask_b32_e64 v91, v57, v41, s[10:11]
	v_cndmask_b32_e64 v90, v56, v40, s[10:11]
	v_mov_b32_dpp v40, v88 row_bcast:15 row_mask:0xa bank_mask:0xf
	s_waitcnt lgkmcnt(2)
	v_pk_mul_f32 v[50:51], v[42:43], v[50:51]
	s_waitcnt lgkmcnt(1)
	v_pk_fma_f32 v[56:57], v[42:43], v[58:59], v[48:49]
	v_cndmask_b32_e64 v43, v51, v43, s[6:7]
	v_cndmask_b32_e64 v42, v50, v42, s[6:7]
	v_cndmask_b32_e64 v49, v57, v49, s[6:7]
	v_cndmask_b32_e64 v48, v56, v48, s[6:7]
	v_mov_b32_dpp v50, v42 row_shr:4 row_mask:0xf bank_mask:0xf
	s_nop 1
	v_mov_b32_dpp v56, v48 row_shr:4 row_mask:0xf bank_mask:0xf
	v_mov_b32_dpp v51, v43 row_shr:4 row_mask:0xf bank_mask:0xf
	v_mov_b32_dpp v57, v49 row_shr:4 row_mask:0xf bank_mask:0xf
	v_mov_b32_dpp v58, v90 row_bcast:15 row_mask:0xa bank_mask:0xf
	v_mov_b32_dpp v41, v89 row_bcast:15 row_mask:0xa bank_mask:0xf
	v_mov_b32_dpp v59, v91 row_bcast:15 row_mask:0xa bank_mask:0xf
	s_waitcnt lgkmcnt(4)
	v_pk_mul_f32 v[50:51], v[42:43], v[50:51]
	s_waitcnt lgkmcnt(3)
	v_pk_fma_f32 v[56:57], v[42:43], v[56:57], v[48:49]
	v_cndmask_b32_e64 v43, v51, v43, s[8:9]
	v_cndmask_b32_e64 v42, v50, v42, s[8:9]
	v_cndmask_b32_e64 v51, v57, v49, s[8:9]
	v_cndmask_b32_e64 v50, v56, v48, s[8:9]
	s_nop 1
	v_mov_b32_dpp v60, v50 row_shr:8 row_mask:0xf bank_mask:0xf
	v_mov_b32_dpp v61, v51 row_shr:8 row_mask:0xf bank_mask:0xf
	v_mov_b32_dpp v56, v42 row_shr:8 row_mask:0xf bank_mask:0xf
	v_mov_b32_dpp v57, v43 row_shr:8 row_mask:0xf bank_mask:0xf
	s_waitcnt lgkmcnt(5)
	v_pk_mul_f32 v[48:49], v[88:89], v[40:41]
	s_waitcnt lgkmcnt(4)
	v_pk_fma_f32 v[40:41], v[88:89], v[58:59], v[90:91]
	s_waitcnt lgkmcnt(2)
	v_pk_fma_f32 v[58:59], v[42:43], v[60:61], v[50:51]
	v_mov_b32_dpp v60, v44 row_shr:1 row_mask:0xf bank_mask:0xf
	v_mov_b32_dpp v61, v45 row_shr:1 row_mask:0xf bank_mask:0xf
	s_waitcnt lgkmcnt(2)
	v_pk_mul_f32 v[56:57], v[42:43], v[56:57]
	v_cndmask_b32_e64 v93, v59, v51, s[10:11]
	v_cndmask_b32_e64 v95, v57, v43, s[10:11]
	v_cndmask_b32_e64 v94, v56, v42, s[10:11]
	s_waitcnt lgkmcnt(0)
	v_pk_fma_f32 v[56:57], v[52:53], v[60:61], v[44:45]
	v_pk_mul_f32 v[42:43], v[52:53], v[154:155]
	v_cndmask_b32_e32 v45, v57, v45, vcc
	v_cndmask_b32_e32 v44, v56, v44, vcc
	s_nop 1
	v_mov_b32_dpp v56, v44 row_shr:2 row_mask:0xf bank_mask:0xf
	v_mov_b32_dpp v57, v45 row_shr:2 row_mask:0xf bank_mask:0xf
	v_cndmask_b32_e32 v43, v43, v53, vcc
	v_cndmask_b32_e32 v42, v42, v52, vcc
	s_nop 1
	v_mov_b32_dpp v52, v42 row_shr:2 row_mask:0xf bank_mask:0xf
	v_mov_b32_dpp v53, v43 row_shr:2 row_mask:0xf bank_mask:0xf
	s_waitcnt lgkmcnt(2)
	v_pk_fma_f32 v[56:57], v[42:43], v[56:57], v[44:45]
	v_cndmask_b32_e64 v92, v58, v50, s[10:11]
	v_cndmask_b32_e64 v45, v57, v45, s[6:7]
	v_cndmask_b32_e64 v44, v56, v44, s[6:7]
	s_nop 1
	v_mov_b32_dpp v56, v44 row_shr:4 row_mask:0xf bank_mask:0xf
	v_mov_b32_dpp v57, v45 row_shr:4 row_mask:0xf bank_mask:0xf
	s_waitcnt lgkmcnt(2)
	v_pk_mul_f32 v[52:53], v[42:43], v[52:53]
	v_mov_b32_dpp v50, v94 row_bcast:15 row_mask:0xa bank_mask:0xf
	v_cndmask_b32_e64 v43, v53, v43, s[6:7]
	v_cndmask_b32_e64 v42, v52, v42, s[6:7]
	s_nop 1
	v_mov_b32_dpp v52, v42 row_shr:4 row_mask:0xf bank_mask:0xf
	v_mov_b32_dpp v53, v43 row_shr:4 row_mask:0xf bank_mask:0xf
	s_waitcnt lgkmcnt(3)
	v_pk_fma_f32 v[56:57], v[42:43], v[56:57], v[44:45]
	v_mov_b32_dpp v51, v95 row_bcast:15 row_mask:0xa bank_mask:0xf
	v_cndmask_b32_e64 v45, v57, v45, s[8:9]
	v_cndmask_b32_e64 v44, v56, v44, s[8:9]
	v_mov_b32_dpp v56, v46 row_shr:1 row_mask:0xf bank_mask:0xf
	v_mov_b32_dpp v57, v47 row_shr:1 row_mask:0xf bank_mask:0xf
	s_waitcnt lgkmcnt(3)
	v_pk_mul_f32 v[52:53], v[42:43], v[52:53]
	v_mov_b32_dpp v60, v44 row_shr:8 row_mask:0xf bank_mask:0xf
	v_cndmask_b32_e64 v43, v53, v43, s[8:9]
	v_cndmask_b32_e64 v42, v52, v42, s[8:9]
	s_waitcnt lgkmcnt(1)
	v_pk_fma_f32 v[56:57], v[54:55], v[56:57], v[46:47]
	v_mov_b32_dpp v52, v42 row_shr:8 row_mask:0xf bank_mask:0xf
	v_mov_b32_dpp v53, v43 row_shr:8 row_mask:0xf bank_mask:0xf
	v_cndmask_b32_e32 v55, v63, v55, vcc
	v_cndmask_b32_e32 v54, v62, v54, vcc
	v_cndmask_b32_e32 v47, v57, v47, vcc
	v_cndmask_b32_e32 v46, v56, v46, vcc
	v_mov_b32_dpp v61, v45 row_shr:8 row_mask:0xf bank_mask:0xf
	v_mov_b32_dpp v56, v54 row_shr:2 row_mask:0xf bank_mask:0xf
	v_mov_b32_dpp v62, v46 row_shr:2 row_mask:0xf bank_mask:0xf
	v_mov_b32_dpp v57, v55 row_shr:2 row_mask:0xf bank_mask:0xf
	v_mov_b32_dpp v63, v47 row_shr:2 row_mask:0xf bank_mask:0xf
	s_waitcnt lgkmcnt(5)
	v_pk_mul_f32 v[52:53], v[42:43], v[52:53]
	s_waitcnt lgkmcnt(4)
	v_pk_fma_f32 v[60:61], v[42:43], v[60:61], v[44:45]
	v_cndmask_b32_e64 v97, v53, v43, s[10:11]
	v_cndmask_b32_e64 v96, v52, v42, s[10:11]
	s_waitcnt lgkmcnt(1)
	v_pk_mul_f32 v[42:43], v[54:55], v[56:57]
	s_waitcnt lgkmcnt(0)
	v_pk_fma_f32 v[52:53], v[54:55], v[62:63], v[46:47]
	v_cndmask_b32_e64 v43, v43, v55, s[6:7]
	v_cndmask_b32_e64 v42, v42, v54, s[6:7]
	v_cndmask_b32_e64 v47, v53, v47, s[6:7]
	v_cndmask_b32_e64 v46, v52, v46, s[6:7]
	v_mov_b32_dpp v52, v42 row_shr:4 row_mask:0xf bank_mask:0xf
	s_nop 1
	v_mov_b32_dpp v54, v46 row_shr:4 row_mask:0xf bank_mask:0xf
	v_mov_b32_dpp v53, v43 row_shr:4 row_mask:0xf bank_mask:0xf
	v_mov_b32_dpp v55, v47 row_shr:4 row_mask:0xf bank_mask:0xf
	v_cndmask_b32_e64 v99, v61, v45, s[10:11]
	v_cndmask_b32_e64 v98, v60, v44, s[10:11]
	v_mov_b32_dpp v58, v92 row_bcast:15 row_mask:0xa bank_mask:0xf
	s_waitcnt lgkmcnt(2)
	v_pk_mul_f32 v[52:53], v[42:43], v[52:53]
	s_waitcnt lgkmcnt(1)
	v_pk_fma_f32 v[54:55], v[42:43], v[54:55], v[46:47]
	v_cndmask_b32_e64 v43, v53, v43, s[8:9]
	v_cndmask_b32_e64 v42, v52, v42, s[8:9]
	v_cndmask_b32_e64 v47, v55, v47, s[8:9]
	v_cndmask_b32_e64 v46, v54, v46, s[8:9]
	v_mov_b32_dpp v52, v42 row_shr:8 row_mask:0xf bank_mask:0xf
	s_nop 1
	v_mov_b32_dpp v54, v46 row_shr:8 row_mask:0xf bank_mask:0xf
	v_mov_b32_dpp v53, v43 row_shr:8 row_mask:0xf bank_mask:0xf
	v_mov_b32_dpp v55, v47 row_shr:8 row_mask:0xf bank_mask:0xf
	v_mov_b32_dpp v59, v93 row_bcast:15 row_mask:0xa bank_mask:0xf
	v_mov_b32_dpp v44, v96 row_bcast:15 row_mask:0xa bank_mask:0xf
	v_mov_b32_dpp v56, v98 row_bcast:15 row_mask:0xa bank_mask:0xf
	s_waitcnt lgkmcnt(4)
	v_pk_mul_f32 v[52:53], v[42:43], v[52:53]
	s_waitcnt lgkmcnt(3)
	v_pk_fma_f32 v[54:55], v[42:43], v[54:55], v[46:47]
	v_cndmask_b32_e64 v101, v53, v43, s[10:11]
	v_cndmask_b32_e64 v100, v52, v42, s[10:11]
	v_cndmask_b32_e64 v103, v55, v47, s[10:11]
	v_cndmask_b32_e64 v102, v54, v46, s[10:11]
	v_mov_b32_dpp v45, v97 row_bcast:15 row_mask:0xa bank_mask:0xf
	v_mov_b32_dpp v57, v99 row_bcast:15 row_mask:0xa bank_mask:0xf
	v_mov_b32_dpp v46, v100 row_bcast:15 row_mask:0xa bank_mask:0xf
	v_mov_b32_dpp v60, v102 row_bcast:15 row_mask:0xa bank_mask:0xf
	v_mov_b32_dpp v47, v101 row_bcast:15 row_mask:0xa bank_mask:0xf
	v_mov_b32_dpp v61, v103 row_bcast:15 row_mask:0xa bank_mask:0xf
	v_pk_mul_f32 v[50:51], v[94:95], v[50:51]
	s_waitcnt lgkmcnt(8)
	v_pk_fma_f32 v[42:43], v[94:95], v[58:59], v[92:93]
	s_waitcnt lgkmcnt(5)
	v_pk_mul_f32 v[52:53], v[96:97], v[44:45]
	s_waitcnt lgkmcnt(4)
	v_pk_fma_f32 v[44:45], v[96:97], v[56:57], v[98:99]
	s_waitcnt lgkmcnt(1)
	v_pk_mul_f32 v[54:55], v[100:101], v[46:47]
	s_waitcnt lgkmcnt(0)
	v_pk_fma_f32 v[46:47], v[100:101], v[60:61], v[102:103]
	v_pk_mul_f32 v[0:1], v[0:1], v[112:113]
	v_pk_mul_f32 v[58:59], v[116:117], v[150:151]
	v_pk_mul_f32 v[0:1], v[0:1], v[120:121]
	s_nop 1
	v_mov_b32_dpp v56, v0 row_shr:1 row_mask:0xf bank_mask:0xf
	v_mov_b32_dpp v57, v1 row_shr:1 row_mask:0xf bank_mask:0xf
	v_cndmask_b32_e32 v59, v59, v117, vcc
	v_cndmask_b32_e32 v58, v58, v116, vcc
	v_pk_mul_f32 v[2:3], v[2:3], v[114:115]
	v_pk_mul_f32 v[4:5], v[4:5], v[124:125]
	s_waitcnt lgkmcnt(0)
	v_pk_fma_f32 v[56:57], v[116:117], v[56:57], v[0:1]
	v_pk_mul_f32 v[2:3], v[2:3], v[122:123]
	v_cndmask_b32_e32 v1, v57, v1, vcc
	v_cndmask_b32_e32 v0, v56, v0, vcc
	v_mov_b32_dpp v56, v58 row_shr:2 row_mask:0xf bank_mask:0xf
	v_mov_b32_dpp v57, v59 row_shr:2 row_mask:0xf bank_mask:0xf
	v_mov_b32_dpp v60, v0 row_shr:2 row_mask:0xf bank_mask:0xf
	v_mov_b32_dpp v61, v1 row_shr:2 row_mask:0xf bank_mask:0xf
	v_mov_b32_dpp v62, v2 row_shr:1 row_mask:0xf bank_mask:0xf
	v_mov_b32_dpp v63, v3 row_shr:1 row_mask:0xf bank_mask:0xf
	s_waitcnt lgkmcnt(4)
	v_pk_mul_f32 v[56:57], v[58:59], v[56:57]
	v_pk_mul_f32 v[4:5], v[4:5], v[128:129]
	s_waitcnt lgkmcnt(2)
	v_pk_fma_f32 v[60:61], v[58:59], v[60:61], v[0:1]
	v_cndmask_b32_e64 v57, v57, v59, s[6:7]
	v_cndmask_b32_e64 v56, v56, v58, s[6:7]
	v_cndmask_b32_e64 v1, v61, v1, s[6:7]
	v_cndmask_b32_e64 v0, v60, v0, s[6:7]
	v_mov_b32_dpp v58, v56 row_shr:4 row_mask:0xf bank_mask:0xf
	v_mov_b32_dpp v59, v57 row_shr:4 row_mask:0xf bank_mask:0xf
	v_mov_b32_dpp v60, v0 row_shr:4 row_mask:0xf bank_mask:0xf
	v_mov_b32_dpp v61, v1 row_shr:4 row_mask:0xf bank_mask:0xf
	v_mov_b32_dpp v112, v4 row_shr:1 row_mask:0xf bank_mask:0xf
	v_mov_b32_dpp v113, v5 row_shr:1 row_mask:0xf bank_mask:0xf
	s_waitcnt lgkmcnt(4)
	v_pk_mul_f32 v[58:59], v[56:57], v[58:59]
	v_pk_mul_f32 v[6:7], v[6:7], v[130:131]
	s_waitcnt lgkmcnt(2)
	v_pk_fma_f32 v[60:61], v[56:57], v[60:61], v[0:1]
	v_cndmask_b32_e64 v57, v59, v57, s[8:9]
	v_cndmask_b32_e64 v56, v58, v56, s[8:9]
	s_nop 1
	v_mov_b32_dpp v58, v56 row_shr:8 row_mask:0xf bank_mask:0xf
	v_mov_b32_dpp v59, v57 row_shr:8 row_mask:0xf bank_mask:0xf
	v_cndmask_b32_e64 v1, v61, v1, s[8:9]
	v_cndmask_b32_e64 v0, v60, v0, s[8:9]
	s_nop 1
	v_mov_b32_dpp v60, v0 row_shr:8 row_mask:0xf bank_mask:0xf
	v_mov_b32_dpp v61, v1 row_shr:8 row_mask:0xf bank_mask:0xf
	s_waitcnt lgkmcnt(2)
	v_pk_mul_f32 v[58:59], v[56:57], v[58:59]
	v_pk_mul_f32 v[6:7], v[6:7], v[134:135]
	v_cndmask_b32_e64 v105, v59, v57, s[10:11]
	v_cndmask_b32_e64 v104, v58, v56, s[10:11]
	s_waitcnt lgkmcnt(0)
	v_pk_fma_f32 v[60:61], v[56:57], v[60:61], v[0:1]
	v_pk_mul_f32 v[56:57], v[118:119], v[148:149]
	v_pk_fma_f32 v[58:59], v[118:119], v[62:63], v[2:3]
	v_cndmask_b32_e32 v57, v57, v119, vcc
	v_cndmask_b32_e32 v56, v56, v118, vcc
	v_cndmask_b32_e32 v3, v59, v3, vcc
	v_cndmask_b32_e32 v2, v58, v2, vcc
	v_mov_b32_dpp v58, v56 row_shr:2 row_mask:0xf bank_mask:0xf
	v_mov_b32_dpp v59, v57 row_shr:2 row_mask:0xf bank_mask:0xf
	v_mov_b32_dpp v62, v2 row_shr:2 row_mask:0xf bank_mask:0xf
	v_mov_b32_dpp v63, v3 row_shr:2 row_mask:0xf bank_mask:0xf
	v_cndmask_b32_e64 v107, v61, v1, s[10:11]
	v_cndmask_b32_e64 v106, v60, v0, s[10:11]
	s_waitcnt lgkmcnt(2)
	v_pk_mul_f32 v[58:59], v[56:57], v[58:59]
	v_mov_b32_dpp v0, v104 row_bcast:15 row_mask:0xa bank_mask:0xf
	s_waitcnt lgkmcnt(1)
	v_pk_fma_f32 v[60:61], v[56:57], v[62:63], v[2:3]
	v_cndmask_b32_e64 v57, v59, v57, s[6:7]
	v_cndmask_b32_e64 v56, v58, v56, s[6:7]
	v_cndmask_b32_e64 v3, v61, v3, s[6:7]
	v_cndmask_b32_e64 v2, v60, v2, s[6:7]
	v_mov_b32_dpp v58, v56 row_shr:4 row_mask:0xf bank_mask:0xf
	v_mov_b32_dpp v59, v57 row_shr:4 row_mask:0xf bank_mask:0xf
	v_mov_b32_dpp v60, v2 row_shr:4 row_mask:0xf bank_mask:0xf
	v_mov_b32_dpp v61, v3 row_shr:4 row_mask:0xf bank_mask:0xf
	v_mov_b32_dpp v62, v106 row_bcast:15 row_mask:0xa bank_mask:0xf
	v_mov_b32_dpp v1, v105 row_bcast:15 row_mask:0xa bank_mask:0xf
	s_waitcnt lgkmcnt(4)
	v_pk_mul_f32 v[58:59], v[56:57], v[58:59]
	v_mov_b32_dpp v63, v107 row_bcast:15 row_mask:0xa bank_mask:0xf
	s_waitcnt lgkmcnt(3)
	v_pk_fma_f32 v[60:61], v[56:57], v[60:61], v[2:3]
	v_cndmask_b32_e64 v59, v59, v57, s[8:9]
	v_cndmask_b32_e64 v58, v58, v56, s[8:9]
	v_cndmask_b32_e64 v3, v61, v3, s[8:9]
	v_cndmask_b32_e64 v2, v60, v2, s[8:9]
	v_mov_b32_dpp v60, v58 row_shr:8 row_mask:0xf bank_mask:0xf
	v_mov_b32_dpp v61, v59 row_shr:8 row_mask:0xf bank_mask:0xf
	v_mov_b32_dpp v108, v2 row_shr:8 row_mask:0xf bank_mask:0xf
	v_mov_b32_dpp v109, v3 row_shr:8 row_mask:0xf bank_mask:0xf
	s_waitcnt lgkmcnt(5)
	v_pk_mul_f32 v[56:57], v[104:105], v[0:1]
	s_waitcnt lgkmcnt(4)
	v_pk_fma_f32 v[0:1], v[104:105], v[62:63], v[106:107]
	s_waitcnt lgkmcnt(2)
	v_pk_mul_f32 v[60:61], v[58:59], v[60:61]
	v_pk_mul_f32 v[114:115], v[132:133], v[136:137]
	s_waitcnt lgkmcnt(0)
	v_pk_fma_f32 v[62:63], v[58:59], v[108:109], v[2:3]
	v_cndmask_b32_e64 v111, v61, v59, s[10:11]
	v_cndmask_b32_e64 v110, v60, v58, s[10:11]
	v_pk_mul_f32 v[58:59], v[126:127], v[146:147]
	v_pk_fma_f32 v[60:61], v[126:127], v[112:113], v[4:5]
	v_cndmask_b32_e32 v59, v59, v127, vcc
	v_cndmask_b32_e32 v58, v58, v126, vcc
	v_cndmask_b32_e32 v5, v61, v5, vcc
	v_cndmask_b32_e32 v4, v60, v4, vcc
	v_mov_b32_dpp v60, v58 row_shr:2 row_mask:0xf bank_mask:0xf
	s_nop 1
	v_mov_b32_dpp v112, v4 row_shr:2 row_mask:0xf bank_mask:0xf
	v_mov_b32_dpp v61, v59 row_shr:2 row_mask:0xf bank_mask:0xf
	v_mov_b32_dpp v113, v5 row_shr:2 row_mask:0xf bank_mask:0xf
	v_cndmask_b32_e64 v109, v63, v3, s[10:11]
	v_cndmask_b32_e64 v108, v62, v2, s[10:11]
	v_mov_b32_dpp v2, v110 row_bcast:15 row_mask:0xa bank_mask:0xf
	s_waitcnt lgkmcnt(2)
	v_pk_mul_f32 v[60:61], v[58:59], v[60:61]
	s_waitcnt lgkmcnt(1)
	v_pk_fma_f32 v[62:63], v[58:59], v[112:113], v[4:5]
	v_cndmask_b32_e64 v61, v61, v59, s[6:7]
	v_cndmask_b32_e64 v60, v60, v58, s[6:7]
	v_cndmask_b32_e64 v5, v63, v5, s[6:7]
	v_cndmask_b32_e64 v4, v62, v4, s[6:7]
	v_mov_b32_dpp v3, v111 row_bcast:15 row_mask:0xa bank_mask:0xf
	v_mov_b32_dpp v62, v60 row_shr:4 row_mask:0xf bank_mask:0xf
	v_mov_b32_dpp v112, v4 row_shr:4 row_mask:0xf bank_mask:0xf
	v_mov_b32_dpp v63, v61 row_shr:4 row_mask:0xf bank_mask:0xf
	v_mov_b32_dpp v113, v5 row_shr:4 row_mask:0xf bank_mask:0xf
	s_waitcnt lgkmcnt(4)
	v_pk_mul_f32 v[58:59], v[110:111], v[2:3]
	v_cndmask_b32_e32 v115, v115, v133, vcc
	v_cndmask_b32_e32 v114, v114, v132, vcc
	s_waitcnt lgkmcnt(1)
	v_pk_mul_f32 v[2:3], v[60:61], v[62:63]
	s_waitcnt lgkmcnt(0)
	v_pk_fma_f32 v[62:63], v[60:61], v[112:113], v[4:5]
	v_cndmask_b32_e64 v3, v3, v61, s[8:9]
	v_cndmask_b32_e64 v5, v63, v5, s[8:9]
	v_cndmask_b32_e64 v4, v62, v4, s[8:9]
	v_mov_b32_dpp v62, v6 row_shr:1 row_mask:0xf bank_mask:0xf
	v_mov_b32_dpp v63, v7 row_shr:1 row_mask:0xf bank_mask:0xf
	v_cndmask_b32_e64 v2, v2, v60, s[8:9]
	s_nop 1
	v_mov_b32_dpp v60, v2 row_shr:8 row_mask:0xf bank_mask:0xf
	v_mov_b32_dpp v61, v3 row_shr:8 row_mask:0xf bank_mask:0xf
	v_mov_b32_dpp v112, v4 row_shr:8 row_mask:0xf bank_mask:0xf
	s_waitcnt lgkmcnt(3)
	v_pk_fma_f32 v[62:63], v[132:133], v[62:63], v[6:7]
	v_mov_b32_dpp v113, v5 row_shr:8 row_mask:0xf bank_mask:0xf
	v_cndmask_b32_e32 v7, v63, v7, vcc
	v_cndmask_b32_e32 v6, v62, v6, vcc
	v_mov_b32_dpp v62, v114 row_shr:2 row_mask:0xf bank_mask:0xf
	s_nop 1
	v_mov_b32_dpp v116, v6 row_shr:2 row_mask:0xf bank_mask:0xf
	v_mov_b32_dpp v63, v115 row_shr:2 row_mask:0xf bank_mask:0xf
	v_mov_b32_dpp v117, v7 row_shr:2 row_mask:0xf bank_mask:0xf
	s_waitcnt lgkmcnt(6)
	v_pk_mul_f32 v[60:61], v[2:3], v[60:61]
	s_waitcnt lgkmcnt(4)
	v_pk_fma_f32 v[118:119], v[2:3], v[112:113], v[4:5]
	v_cndmask_b32_e64 v113, v61, v3, s[10:11]
	v_cndmask_b32_e64 v112, v60, v2, s[10:11]
	s_waitcnt lgkmcnt(1)
	v_pk_mul_f32 v[2:3], v[114:115], v[62:63]
	s_waitcnt lgkmcnt(0)
	v_pk_fma_f32 v[60:61], v[114:115], v[116:117], v[6:7]
	v_cndmask_b32_e64 v3, v3, v115, s[6:7]
	v_cndmask_b32_e64 v2, v2, v114, s[6:7]
	v_cndmask_b32_e64 v7, v61, v7, s[6:7]
	v_cndmask_b32_e64 v6, v60, v6, s[6:7]
	v_mov_b32_dpp v60, v2 row_shr:4 row_mask:0xf bank_mask:0xf
	s_nop 1
	v_mov_b32_dpp v62, v6 row_shr:4 row_mask:0xf bank_mask:0xf
	v_mov_b32_dpp v61, v3 row_shr:4 row_mask:0xf bank_mask:0xf
	v_mov_b32_dpp v63, v7 row_shr:4 row_mask:0xf bank_mask:0xf
	v_cndmask_b32_e64 v115, v119, v5, s[10:11]
	v_cndmask_b32_e64 v114, v118, v4, s[10:11]
	v_mov_b32_dpp v120, v108 row_bcast:15 row_mask:0xa bank_mask:0xf
	s_waitcnt lgkmcnt(2)
	v_pk_mul_f32 v[60:61], v[2:3], v[60:61]
	s_waitcnt lgkmcnt(1)
	v_pk_fma_f32 v[62:63], v[2:3], v[62:63], v[6:7]
	v_cndmask_b32_e64 v3, v61, v3, s[8:9]
	v_cndmask_b32_e64 v2, v60, v2, s[8:9]
	v_cndmask_b32_e64 v7, v63, v7, s[8:9]
	v_cndmask_b32_e64 v6, v62, v6, s[8:9]
	v_mov_b32_dpp v60, v2 row_shr:8 row_mask:0xf bank_mask:0xf
	s_nop 1
	v_mov_b32_dpp v62, v6 row_shr:8 row_mask:0xf bank_mask:0xf
	v_mov_b32_dpp v61, v3 row_shr:8 row_mask:0xf bank_mask:0xf
	v_mov_b32_dpp v63, v7 row_shr:8 row_mask:0xf bank_mask:0xf
	v_mov_b32_dpp v121, v109 row_bcast:15 row_mask:0xa bank_mask:0xf
	v_mov_b32_dpp v4, v112 row_bcast:15 row_mask:0xa bank_mask:0xf
	v_mov_b32_dpp v122, v114 row_bcast:15 row_mask:0xa bank_mask:0xf
	s_waitcnt lgkmcnt(4)
	v_pk_mul_f32 v[60:61], v[2:3], v[60:61]
	s_waitcnt lgkmcnt(3)
	v_pk_fma_f32 v[62:63], v[2:3], v[62:63], v[6:7]
	v_cndmask_b32_e64 v117, v61, v3, s[10:11]
	v_cndmask_b32_e64 v116, v60, v2, s[10:11]
	v_cndmask_b32_e64 v119, v63, v7, s[10:11]
	v_cndmask_b32_e64 v118, v62, v6, s[10:11]
	v_mov_b32_dpp v5, v113 row_bcast:15 row_mask:0xa bank_mask:0xf
	v_mov_b32_dpp v123, v115 row_bcast:15 row_mask:0xa bank_mask:0xf
	v_mov_b32_dpp v6, v116 row_bcast:15 row_mask:0xa bank_mask:0xf
	v_mov_b32_dpp v124, v118 row_bcast:15 row_mask:0xa bank_mask:0xf
	v_mov_b32_dpp v7, v117 row_bcast:15 row_mask:0xa bank_mask:0xf
	v_mov_b32_dpp v125, v119 row_bcast:15 row_mask:0xa bank_mask:0xf
	s_waitcnt lgkmcnt(8)
	v_pk_fma_f32 v[2:3], v[110:111], v[120:121], v[108:109]
	s_waitcnt lgkmcnt(5)
	v_pk_mul_f32 v[60:61], v[112:113], v[4:5]
	s_waitcnt lgkmcnt(4)
	v_pk_fma_f32 v[4:5], v[112:113], v[122:123], v[114:115]
	s_waitcnt lgkmcnt(1)
	v_pk_mul_f32 v[62:63], v[116:117], v[6:7]
	s_waitcnt lgkmcnt(0)
	v_pk_fma_f32 v[6:7], v[116:117], v[124:125], v[118:119]
	v_cmp_eq_u32_e64 s[6:7], 31, v162
	v_and_b32_e32 v122, 0xffffffc0, v160
	s_and_saveexec_b64 s[2:3], s[6:7]
	s_cbranch_execz .LBB0_906
	v_or_b32_e32 v120, v164, v122
	v_lshl_add_u32 v120, v120, 2, s89
	ds_write_b128 v120, v[8:11] offset:34816
	ds_write_b128 v120, v[12:15] offset:35840
	ds_write_b128 v120, v[20:23] offset:34848
	ds_write_b128 v120, v[16:19] offset:35872
	ds_write_b128 v120, v[28:31] offset:34880
	ds_write_b128 v120, v[24:27] offset:35904
	ds_write_b128 v120, v[36:39] offset:34912
	ds_write_b128 v120, v[32:35] offset:35936
	ds_write_b128 v120, v[48:51] offset:34944
	ds_write_b128 v120, v[40:43] offset:35968
	ds_write_b128 v120, v[52:55] offset:34976
	ds_write_b128 v120, v[44:47] offset:36000
	ds_write_b128 v120, v[56:59] offset:35008
	ds_write_b128 v120, v[0:3] offset:36032
	ds_write_b128 v120, v[60:63] offset:35040
	ds_write_b128 v120, v[4:7] offset:36064
